# speedup vs baseline: 1.1067x; 1.0095x over previous
; DI float bflo(unsigned v) { return __uint_as_float(v << 16); }
; DI float bfhi(unsigned v) { return __uint_as_float(v & 0xffff0000u); }
; template <int MASK>
; __global__ void __launch_bounds__(256, 2) fwd_megakernel_t(Params p) {
;     ...
;           const u16* gn = gbuf + ((size_t)((((br * 128 + mt) * 16 + nt) * 4 + wave) * 64 + lane)) * 64;
;           const u16* gd = gbuf + ((size_t)(((((br < 2 ? br + 1 : 2) * 128 + mt) * 16 + nt) * 4 + wave) * 64 + lane)) * 64;
; #pragma unroll
;           for (int i = 0; i < 2; i++)
; #pragma unroll
;             for (int j = 0; j < 2; j++) {
;               const uint4 n0v = *(const uint4*)(gn + (i * 2 + j) * 16), n1v = *(const uint4*)(gn + (i * 2 + j) * 16 + 8);
;               const uint4 d0v = *(const uint4*)(gd + (i * 2 + j) * 16), d1v = *(const uint4*)(gd + (i * 2 + j) * 16 + 8);
;               const unsigned nw[8] = {n0v.x, n0v.y, n0v.z, n0v.w, n1v.x, n1v.y, n1v.z, n1v.w};
;               const unsigned dw[8] = {d0v.x, d0v.y, d0v.z, d0v.w, d1v.x, d1v.y, d1v.z, d1v.w};
; #pragma unroll
;               for (int q = 0; q < 8; q++) {
;                 const float na = fmaxf(bflo(nw[q]), 1e-30f), nb = fmaxf(bfhi(nw[q]), 1e-30f);
;                 const float da = (br < 2) ? fmaxf(bflo(dw[q]), 1e-30f) : 1.f, db = (br < 2) ? fmaxf(bfhi(dw[q]), 1e-30f) : 1.f;
;                 acc[i][j][2 * q] *= na * __builtin_amdgcn_rcpf(da);
;                 acc[i][j][2 * q + 1] *= nb * __builtin_amdgcn_rcpf(db);
;               }
;             }
.LBB0_398:
	s_add_i32 s5, s14, 1
	s_lshl_b32 s15, s5, 7
	s_cmp_eq_u32 s14, 2
	s_cselect_b64 s[6:7], -1, 0
	s_waitcnt vmcnt(7)
	v_lshl_add_u32 v64, s14, 19, v206
	s_and_b64 s[8:9], s[6:7], exec
	v_ashrrev_i32_e32 v65, 31, v64
	s_cselect_b32 s8, 0x100, s15
	v_lshlrev_b64 v[64:65], 7, v[64:65]
	s_add_i32 s8, s8, s10
	s_waitcnt vmcnt(1)
	v_lshl_add_u64 v[98:99], s[86:87], 0, v[64:65]
	v_lshl_add_u32 v64, s8, 12, v207
	v_or_b32_e32 v64, v64, v154
	v_ashrrev_i32_e32 v65, 31, v64
	v_lshlrev_b64 v[64:65], 7, v[64:65]
	v_lshl_add_u64 v[96:97], s[86:87], 0, v[64:65]
	v_mul_u32_u24_e32 v104, 0x70, v154
	v_sub_u32_e32 v104, 0x1000, v104
	v_ashrrev_i32_e32 v105, 31, v104
	v_lshl_add_u64 v[98:99], v[98:99], 0, v[104:105]
	v_lshl_add_u64 v[96:97], v[96:97], 0, v[104:105]
	global_load_dwordx4 v[64:67], v[98:99], off offset:-1024
	global_load_dwordx4 v[72:75], v[98:99], off offset:-2048
	global_load_dwordx4 v[80:83], v[98:99], off offset:-3072
	global_load_dwordx4 v[88:91], v[98:99], off offset:-4096
	global_load_dwordx4 v[68:71], v[96:97], off offset:-1024
	global_load_dwordx4 v[76:79], v[96:97], off offset:-2048
	global_load_dwordx4 v[84:87], v[96:97], off offset:-3072
	global_load_dwordx4 v[92:95], v[96:97], off offset:-4096
	s_cmp_eq_u32 s5, 3
	s_mov_b32 s14, s5
	s_waitcnt vmcnt(4)
	v_lshlrev_b32_e32 v100, 16, v88
	v_and_b32_e32 v88, 0xffff0000, v88
	v_max_f32_e32 v88, v88, v88
	v_max_f32_e32 v101, 0xda24260, v88
	s_waitcnt vmcnt(0)
	v_lshlrev_b32_e32 v88, 16, v92
	v_and_b32_e32 v92, 0xffff0000, v92
	v_max_f32_e32 v92, v92, v92
	v_max_f32_e32 v92, 0xda24260, v92
	v_cndmask_b32_e64 v92, v92, 1.0, s[6:7]
	v_rcp_f32_e32 v103, v92
	v_lshlrev_b32_e32 v92, 16, v93
	v_and_b32_e32 v93, 0xffff0000, v93
	v_max_f32_e32 v92, v92, v92
	v_max_f32_e32 v93, v93, v93
	v_max_f32_e32 v88, v88, v88
	v_max_f32_e32 v92, 0xda24260, v92
	v_max_f32_e32 v93, 0xda24260, v93
	v_max_f32_e32 v88, 0xda24260, v88
	v_cndmask_b32_e64 v92, v92, 1.0, s[6:7]
	v_cndmask_b32_e64 v93, v93, 1.0, s[6:7]
	v_cndmask_b32_e64 v88, v88, 1.0, s[6:7]
	v_rcp_f32_e32 v92, v92
	v_rcp_f32_e32 v93, v93
	v_rcp_f32_e32 v102, v88
	v_lshlrev_b32_e32 v88, 16, v89
	v_and_b32_e32 v89, 0xffff0000, v89
	v_max_f32_e32 v88, v88, v88
	v_max_f32_e32 v89, v89, v89
	v_max_f32_e32 v88, 0xda24260, v88
	v_max_f32_e32 v89, 0xda24260, v89
	v_pk_mul_f32 v[88:89], v[88:89], v[92:93]
	v_and_b32_e32 v92, 0xffff0000, v94
	v_pk_mul_f32 v[50:51], v[88:89], v[50:51]
	v_lshlrev_b32_e32 v88, 16, v90
	v_and_b32_e32 v89, 0xffff0000, v90
	v_lshlrev_b32_e32 v90, 16, v94
	v_max_f32_e32 v90, v90, v90
	v_max_f32_e32 v92, v92, v92
	v_max_f32_e32 v90, 0xda24260, v90
	v_max_f32_e32 v92, 0xda24260, v92
	v_cndmask_b32_e64 v90, v90, 1.0, s[6:7]
	v_cndmask_b32_e64 v93, v92, 1.0, s[6:7]
	v_rcp_f32_e32 v92, v90
	v_rcp_f32_e32 v93, v93
	v_max_f32_e32 v88, v88, v88
	v_max_f32_e32 v89, v89, v89
	v_max_f32_e32 v88, 0xda24260, v88
	v_max_f32_e32 v89, 0xda24260, v89
	v_pk_mul_f32 v[88:89], v[88:89], v[92:93]
	v_lshlrev_b32_e32 v90, 16, v95
	v_pk_mul_f32 v[52:53], v[88:89], v[52:53]
	v_lshlrev_b32_e32 v88, 16, v91
	v_and_b32_e32 v89, 0xffff0000, v91
	v_and_b32_e32 v91, 0xffff0000, v95
	v_max_f32_e32 v90, v90, v90
	v_max_f32_e32 v91, v91, v91
	v_max_f32_e32 v90, 0xda24260, v90
	v_max_f32_e32 v91, 0xda24260, v91
	v_cndmask_b32_e64 v90, v90, 1.0, s[6:7]
	v_cndmask_b32_e64 v91, v91, 1.0, s[6:7]
	v_rcp_f32_e32 v90, v90
	v_rcp_f32_e32 v91, v91
	v_max_f32_e32 v88, v88, v88
	v_max_f32_e32 v89, v89, v89
	v_max_f32_e32 v88, 0xda24260, v88
	v_max_f32_e32 v89, 0xda24260, v89
	v_pk_mul_f32 v[88:89], v[88:89], v[90:91]
	v_max_f32_e32 v100, v100, v100
	v_pk_mul_f32 v[54:55], v[88:89], v[54:55]
	v_lshlrev_b32_e32 v88, 16, v80
	v_and_b32_e32 v80, 0xffff0000, v80
	v_max_f32_e32 v80, v80, v80
	v_max_f32_e32 v89, 0xda24260, v80
	v_lshlrev_b32_e32 v80, 16, v84
	v_and_b32_e32 v84, 0xffff0000, v84
	v_max_f32_e32 v84, v84, v84
	v_max_f32_e32 v84, 0xda24260, v84
	v_cndmask_b32_e64 v84, v84, 1.0, s[6:7]
	v_rcp_f32_e32 v91, v84
	v_lshlrev_b32_e32 v84, 16, v85
	v_and_b32_e32 v85, 0xffff0000, v85
	v_max_f32_e32 v84, v84, v84
	v_max_f32_e32 v85, v85, v85
	v_max_f32_e32 v80, v80, v80
	v_max_f32_e32 v84, 0xda24260, v84
	v_max_f32_e32 v85, 0xda24260, v85
	v_max_f32_e32 v80, 0xda24260, v80
	v_cndmask_b32_e64 v84, v84, 1.0, s[6:7]
	v_cndmask_b32_e64 v85, v85, 1.0, s[6:7]
	v_cndmask_b32_e64 v80, v80, 1.0, s[6:7]
	v_rcp_f32_e32 v84, v84
	v_rcp_f32_e32 v85, v85
	v_rcp_f32_e32 v90, v80
	v_lshlrev_b32_e32 v80, 16, v81
	v_and_b32_e32 v81, 0xffff0000, v81
	v_max_f32_e32 v80, v80, v80
	v_max_f32_e32 v81, v81, v81
	v_max_f32_e32 v80, 0xda24260, v80
	v_max_f32_e32 v81, 0xda24260, v81
	v_pk_mul_f32 v[80:81], v[80:81], v[84:85]
	v_and_b32_e32 v84, 0xffff0000, v86
	v_pk_mul_f32 v[58:59], v[80:81], v[58:59]
	v_lshlrev_b32_e32 v80, 16, v82
	v_and_b32_e32 v81, 0xffff0000, v82
	v_lshlrev_b32_e32 v82, 16, v86
	v_max_f32_e32 v82, v82, v82
	v_max_f32_e32 v84, v84, v84
	v_max_f32_e32 v82, 0xda24260, v82
	v_max_f32_e32 v84, 0xda24260, v84
	v_cndmask_b32_e64 v82, v82, 1.0, s[6:7]
	v_cndmask_b32_e64 v85, v84, 1.0, s[6:7]
	v_rcp_f32_e32 v84, v82
	v_rcp_f32_e32 v85, v85
	v_max_f32_e32 v80, v80, v80
	v_max_f32_e32 v81, v81, v81
	v_max_f32_e32 v80, 0xda24260, v80
	v_max_f32_e32 v81, 0xda24260, v81
	v_pk_mul_f32 v[80:81], v[80:81], v[84:85]
	v_lshlrev_b32_e32 v82, 16, v87
	v_pk_mul_f32 v[60:61], v[80:81], v[60:61]
	v_lshlrev_b32_e32 v80, 16, v83
	v_and_b32_e32 v81, 0xffff0000, v83
	v_and_b32_e32 v83, 0xffff0000, v87
	v_max_f32_e32 v82, v82, v82
	v_max_f32_e32 v83, v83, v83
	v_max_f32_e32 v82, 0xda24260, v82
	v_max_f32_e32 v83, 0xda24260, v83
	v_cndmask_b32_e64 v82, v82, 1.0, s[6:7]
	v_cndmask_b32_e64 v83, v83, 1.0, s[6:7]
; DI float bflo(unsigned v) { return __uint_as_float(v << 16); }
; DI float bfhi(unsigned v) { return __uint_as_float(v & 0xffff0000u); }
; template <int MASK>
; __global__ void __launch_bounds__(256, 2) fwd_megakernel_t(Params p) {
;     ...
;           const u16* gn = gbuf + ((size_t)((((br * 128 + mt) * 16 + nt) * 4 + wave) * 64 + lane)) * 64;
;           const u16* gd = gbuf + ((size_t)(((((br < 2 ? br + 1 : 2) * 128 + mt) * 16 + nt) * 4 + wave) * 64 + lane)) * 64;
; #pragma unroll
;           for (int i = 0; i < 2; i++)
; #pragma unroll
;             for (int j = 0; j < 2; j++) {
;               const uint4 n0v = *(const uint4*)(gn + (i * 2 + j) * 16), n1v = *(const uint4*)(gn + (i * 2 + j) * 16 + 8);
;               const uint4 d0v = *(const uint4*)(gd + (i * 2 + j) * 16), d1v = *(const uint4*)(gd + (i * 2 + j) * 16 + 8);
;               const unsigned nw[8] = {n0v.x, n0v.y, n0v.z, n0v.w, n1v.x, n1v.y, n1v.z, n1v.w};
;               const unsigned dw[8] = {d0v.x, d0v.y, d0v.z, d0v.w, d1v.x, d1v.y, d1v.z, d1v.w};
; #pragma unroll
;               for (int q = 0; q < 8; q++) {
;                 const float na = fmaxf(bflo(nw[q]), 1e-30f), nb = fmaxf(bfhi(nw[q]), 1e-30f);
;                 const float da = (br < 2) ? fmaxf(bflo(dw[q]), 1e-30f) : 1.f, db = (br < 2) ? fmaxf(bfhi(dw[q]), 1e-30f) : 1.f;
;                 acc[i][j][2 * q] *= na * __builtin_amdgcn_rcpf(da);
;                 acc[i][j][2 * q + 1] *= nb * __builtin_amdgcn_rcpf(db);
;               }
;             }
	v_rcp_f32_e32 v82, v82
	v_rcp_f32_e32 v83, v83
	v_max_f32_e32 v80, v80, v80
	v_max_f32_e32 v81, v81, v81
	v_max_f32_e32 v80, 0xda24260, v80
	v_max_f32_e32 v81, 0xda24260, v81
	v_pk_mul_f32 v[80:81], v[80:81], v[82:83]
	v_max_f32_e32 v88, v88, v88
	v_pk_mul_f32 v[62:63], v[80:81], v[62:63]
	v_lshlrev_b32_e32 v80, 16, v72
	v_and_b32_e32 v72, 0xffff0000, v72
	v_max_f32_e32 v72, v72, v72
	v_max_f32_e32 v81, 0xda24260, v72
	v_lshlrev_b32_e32 v72, 16, v76
	v_and_b32_e32 v76, 0xffff0000, v76
	v_max_f32_e32 v76, v76, v76
	v_max_f32_e32 v76, 0xda24260, v76
	v_cndmask_b32_e64 v76, v76, 1.0, s[6:7]
	v_rcp_f32_e32 v83, v76
	v_lshlrev_b32_e32 v76, 16, v77
	v_and_b32_e32 v77, 0xffff0000, v77
	v_max_f32_e32 v76, v76, v76
	v_max_f32_e32 v77, v77, v77
	v_max_f32_e32 v72, v72, v72
	v_max_f32_e32 v76, 0xda24260, v76
	v_max_f32_e32 v77, 0xda24260, v77
	v_max_f32_e32 v72, 0xda24260, v72
	v_cndmask_b32_e64 v76, v76, 1.0, s[6:7]
	v_cndmask_b32_e64 v77, v77, 1.0, s[6:7]
	v_cndmask_b32_e64 v72, v72, 1.0, s[6:7]
	v_rcp_f32_e32 v76, v76
	v_rcp_f32_e32 v77, v77
	v_rcp_f32_e32 v82, v72
	v_lshlrev_b32_e32 v72, 16, v73
	v_and_b32_e32 v73, 0xffff0000, v73
	v_max_f32_e32 v72, v72, v72
	v_max_f32_e32 v73, v73, v73
	v_max_f32_e32 v72, 0xda24260, v72
	v_max_f32_e32 v73, 0xda24260, v73
	v_pk_mul_f32 v[72:73], v[72:73], v[76:77]
	v_and_b32_e32 v76, 0xffff0000, v78
	v_pk_mul_f32 v[34:35], v[72:73], v[34:35]
	v_lshlrev_b32_e32 v72, 16, v74
	v_and_b32_e32 v73, 0xffff0000, v74
	v_lshlrev_b32_e32 v74, 16, v78
	v_max_f32_e32 v74, v74, v74
	v_max_f32_e32 v76, v76, v76
	v_max_f32_e32 v74, 0xda24260, v74
	v_max_f32_e32 v76, 0xda24260, v76
	v_cndmask_b32_e64 v74, v74, 1.0, s[6:7]
	v_cndmask_b32_e64 v77, v76, 1.0, s[6:7]
	v_rcp_f32_e32 v76, v74
	v_rcp_f32_e32 v77, v77
	v_max_f32_e32 v72, v72, v72
	v_max_f32_e32 v73, v73, v73
	v_max_f32_e32 v72, 0xda24260, v72
	v_max_f32_e32 v73, 0xda24260, v73
	v_pk_mul_f32 v[72:73], v[72:73], v[76:77]
	v_lshlrev_b32_e32 v74, 16, v79
	v_pk_mul_f32 v[36:37], v[72:73], v[36:37]
	v_lshlrev_b32_e32 v72, 16, v75
	v_and_b32_e32 v73, 0xffff0000, v75
	v_and_b32_e32 v75, 0xffff0000, v79
	v_max_f32_e32 v74, v74, v74
	v_max_f32_e32 v75, v75, v75
	v_max_f32_e32 v74, 0xda24260, v74
	v_max_f32_e32 v75, 0xda24260, v75
	v_cndmask_b32_e64 v74, v74, 1.0, s[6:7]
	v_cndmask_b32_e64 v75, v75, 1.0, s[6:7]
	v_rcp_f32_e32 v74, v74
	v_rcp_f32_e32 v75, v75
	v_max_f32_e32 v72, v72, v72
	v_max_f32_e32 v73, v73, v73
	v_max_f32_e32 v72, 0xda24260, v72
	v_max_f32_e32 v73, 0xda24260, v73
	v_pk_mul_f32 v[72:73], v[72:73], v[74:75]
	v_max_f32_e32 v80, v80, v80
	v_pk_mul_f32 v[38:39], v[72:73], v[38:39]
	v_lshlrev_b32_e32 v72, 16, v64
	v_and_b32_e32 v64, 0xffff0000, v64
	v_max_f32_e32 v64, v64, v64
	v_max_f32_e32 v73, 0xda24260, v64
	v_lshlrev_b32_e32 v64, 16, v68
	v_and_b32_e32 v68, 0xffff0000, v68
	v_max_f32_e32 v68, v68, v68
	v_max_f32_e32 v68, 0xda24260, v68
	v_cndmask_b32_e64 v68, v68, 1.0, s[6:7]
	v_rcp_f32_e32 v75, v68
	v_lshlrev_b32_e32 v68, 16, v69
	v_and_b32_e32 v69, 0xffff0000, v69
	v_max_f32_e32 v68, v68, v68
	v_max_f32_e32 v69, v69, v69
	v_max_f32_e32 v64, v64, v64
	v_max_f32_e32 v68, 0xda24260, v68
	v_max_f32_e32 v69, 0xda24260, v69
	v_max_f32_e32 v64, 0xda24260, v64
	v_cndmask_b32_e64 v68, v68, 1.0, s[6:7]
	v_cndmask_b32_e64 v69, v69, 1.0, s[6:7]
	v_cndmask_b32_e64 v64, v64, 1.0, s[6:7]
	v_rcp_f32_e32 v68, v68
	v_rcp_f32_e32 v69, v69
	v_rcp_f32_e32 v74, v64
	v_lshlrev_b32_e32 v64, 16, v65
	v_and_b32_e32 v65, 0xffff0000, v65
	v_max_f32_e32 v64, v64, v64
	v_max_f32_e32 v65, v65, v65
	v_max_f32_e32 v64, 0xda24260, v64
	v_max_f32_e32 v65, 0xda24260, v65
	v_pk_mul_f32 v[64:65], v[64:65], v[68:69]
	v_and_b32_e32 v68, 0xffff0000, v70
	v_pk_mul_f32 v[42:43], v[64:65], v[42:43]
	v_lshlrev_b32_e32 v64, 16, v66
	v_and_b32_e32 v65, 0xffff0000, v66
	v_lshlrev_b32_e32 v66, 16, v70
	v_max_f32_e32 v66, v66, v66
	v_max_f32_e32 v68, v68, v68
	v_max_f32_e32 v66, 0xda24260, v66
	v_max_f32_e32 v68, 0xda24260, v68
	v_cndmask_b32_e64 v66, v66, 1.0, s[6:7]
	v_cndmask_b32_e64 v69, v68, 1.0, s[6:7]
	v_rcp_f32_e32 v68, v66
	v_rcp_f32_e32 v69, v69
	v_max_f32_e32 v64, v64, v64
	v_max_f32_e32 v65, v65, v65
	v_max_f32_e32 v64, 0xda24260, v64
	v_max_f32_e32 v65, 0xda24260, v65
	v_pk_mul_f32 v[64:65], v[64:65], v[68:69]
	v_lshlrev_b32_e32 v66, 16, v71
	v_pk_mul_f32 v[44:45], v[64:65], v[44:45]
	v_lshlrev_b32_e32 v64, 16, v67
	v_and_b32_e32 v65, 0xffff0000, v67
	v_and_b32_e32 v67, 0xffff0000, v71
	v_max_f32_e32 v66, v66, v66
	v_max_f32_e32 v67, v67, v67
	v_max_f32_e32 v66, 0xda24260, v66
	v_max_f32_e32 v67, 0xda24260, v67
	v_cndmask_b32_e64 v66, v66, 1.0, s[6:7]
	v_cndmask_b32_e64 v67, v67, 1.0, s[6:7]
	v_rcp_f32_e32 v66, v66
	v_rcp_f32_e32 v67, v67
	v_max_f32_e32 v72, v72, v72
	v_max_f32_e32 v64, v64, v64
	v_max_f32_e32 v65, v65, v65
	v_max_f32_e32 v88, 0xda24260, v88
	v_max_f32_e32 v80, 0xda24260, v80
	v_max_f32_e32 v72, 0xda24260, v72
	v_max_f32_e32 v64, 0xda24260, v64
	v_max_f32_e32 v65, 0xda24260, v65
	v_pk_mul_f32 v[88:89], v[88:89], v[90:91]
	v_pk_mul_f32 v[80:81], v[80:81], v[82:83]
	v_pk_mul_f32 v[72:73], v[72:73], v[74:75]
	v_pk_mul_f32 v[64:65], v[64:65], v[66:67]
	v_pk_mul_f32 v[56:57], v[88:89], v[56:57]
	v_pk_mul_f32 v[32:33], v[80:81], v[32:33]
	v_pk_mul_f32 v[40:41], v[72:73], v[40:41]
	v_pk_mul_f32 v[46:47], v[64:65], v[46:47]
	global_load_dwordx4 v[64:67], v[98:99], off offset:3072
	global_load_dwordx4 v[68:71], v[98:99], off offset:2048
	global_load_dwordx4 v[80:83], v[98:99], off offset:1024
	global_load_dwordx4 v[92:95], v[98:99], off offset:0
	global_load_dwordx4 v[72:75], v[96:97], off offset:3072
	global_load_dwordx4 v[76:79], v[96:97], off offset:2048
	global_load_dwordx4 v[84:87], v[96:97], off offset:1024
	global_load_dwordx4 v[88:91], v[96:97], off offset:0
	v_max_f32_e32 v100, 0xda24260, v100
	v_pk_mul_f32 v[100:101], v[100:101], v[102:103]
	s_waitcnt vmcnt(4)
; DI float bflo(unsigned v) { return __uint_as_float(v << 16); }
; DI float bfhi(unsigned v) { return __uint_as_float(v & 0xffff0000u); }
; template <int MASK>
; __global__ void __launch_bounds__(256, 2) fwd_megakernel_t(Params p) {
;     ...
;           const u16* gn = gbuf + ((size_t)((((br * 128 + mt) * 16 + nt) * 4 + wave) * 64 + lane)) * 64;
;           const u16* gd = gbuf + ((size_t)(((((br < 2 ? br + 1 : 2) * 128 + mt) * 16 + nt) * 4 + wave) * 64 + lane)) * 64;
; #pragma unroll
;           for (int i = 0; i < 2; i++)
; #pragma unroll
;             for (int j = 0; j < 2; j++) {
;               const uint4 n0v = *(const uint4*)(gn + (i * 2 + j) * 16), n1v = *(const uint4*)(gn + (i * 2 + j) * 16 + 8);
;               const uint4 d0v = *(const uint4*)(gd + (i * 2 + j) * 16), d1v = *(const uint4*)(gd + (i * 2 + j) * 16 + 8);
;               const unsigned nw[8] = {n0v.x, n0v.y, n0v.z, n0v.w, n1v.x, n1v.y, n1v.z, n1v.w};
;               const unsigned dw[8] = {d0v.x, d0v.y, d0v.z, d0v.w, d1v.x, d1v.y, d1v.z, d1v.w};
; #pragma unroll
;               for (int q = 0; q < 8; q++) {
;                 const float na = fmaxf(bflo(nw[q]), 1e-30f), nb = fmaxf(bfhi(nw[q]), 1e-30f);
;                 const float da = (br < 2) ? fmaxf(bflo(dw[q]), 1e-30f) : 1.f, db = (br < 2) ? fmaxf(bfhi(dw[q]), 1e-30f) : 1.f;
;                 acc[i][j][2 * q] *= na * __builtin_amdgcn_rcpf(da);
;                 acc[i][j][2 * q + 1] *= nb * __builtin_amdgcn_rcpf(db);
;               }
;             }
	v_lshlrev_b32_e32 v96, 16, v92
	v_and_b32_e32 v92, 0xffff0000, v92
	v_max_f32_e32 v92, v92, v92
	v_max_f32_e32 v97, 0xda24260, v92
	s_waitcnt vmcnt(0)
	v_lshlrev_b32_e32 v92, 16, v88
	v_and_b32_e32 v88, 0xffff0000, v88
	v_max_f32_e32 v88, v88, v88
	v_max_f32_e32 v88, 0xda24260, v88
	v_max_f32_e32 v92, v92, v92
	v_cndmask_b32_e64 v88, v88, 1.0, s[6:7]
	v_max_f32_e32 v92, 0xda24260, v92
	v_rcp_f32_e32 v99, v88
	v_lshlrev_b32_e32 v88, 16, v93
	v_cndmask_b32_e64 v92, v92, 1.0, s[6:7]
	v_max_f32_e32 v88, v88, v88
	v_rcp_f32_e32 v98, v92
	v_max_f32_e32 v92, 0xda24260, v88
	v_and_b32_e32 v88, 0xffff0000, v93
	v_max_f32_e32 v88, v88, v88
	v_max_f32_e32 v93, 0xda24260, v88
	v_lshlrev_b32_e32 v88, 16, v89
	v_and_b32_e32 v89, 0xffff0000, v89
	v_max_f32_e32 v88, v88, v88
	v_max_f32_e32 v89, v89, v89
	v_max_f32_e32 v88, 0xda24260, v88
	v_max_f32_e32 v89, 0xda24260, v89
	v_cndmask_b32_e64 v88, v88, 1.0, s[6:7]
	v_cndmask_b32_e64 v89, v89, 1.0, s[6:7]
	v_rcp_f32_e32 v88, v88
	v_rcp_f32_e32 v89, v89
	v_max_f32_e32 v96, v96, v96
	v_max_f32_e32 v96, 0xda24260, v96
	v_pk_mul_f32 v[96:97], v[96:97], v[98:99]
	v_pk_mul_f32 v[88:89], v[92:93], v[88:89]
	v_lshlrev_b32_e32 v92, 16, v90
	v_and_b32_e32 v90, 0xffff0000, v90
	v_max_f32_e32 v92, v92, v92
	v_max_f32_e32 v90, v90, v90
	v_max_f32_e32 v92, 0xda24260, v92
	v_max_f32_e32 v90, 0xda24260, v90
	v_cndmask_b32_e64 v92, v92, 1.0, s[6:7]
	v_cndmask_b32_e64 v90, v90, 1.0, s[6:7]
	v_rcp_f32_e32 v92, v92
	v_rcp_f32_e32 v93, v90
	v_lshlrev_b32_e32 v90, 16, v91
	v_and_b32_e32 v91, 0xffff0000, v91
	v_pk_mul_f32 v[18:19], v[88:89], v[18:19]
	v_lshlrev_b32_e32 v88, 16, v94
	v_and_b32_e32 v89, 0xffff0000, v94
	v_max_f32_e32 v90, v90, v90
	v_max_f32_e32 v91, v91, v91
	v_max_f32_e32 v88, v88, v88
	v_max_f32_e32 v89, v89, v89
	v_max_f32_e32 v90, 0xda24260, v90
	v_max_f32_e32 v91, 0xda24260, v91
	v_max_f32_e32 v88, 0xda24260, v88
	v_max_f32_e32 v89, 0xda24260, v89
	v_cndmask_b32_e64 v90, v90, 1.0, s[6:7]
	v_cndmask_b32_e64 v91, v91, 1.0, s[6:7]
	v_pk_mul_f32 v[88:89], v[88:89], v[92:93]
	v_rcp_f32_e32 v90, v90
	v_rcp_f32_e32 v91, v91
	v_pk_mul_f32 v[20:21], v[88:89], v[20:21]
	v_lshlrev_b32_e32 v88, 16, v95
	v_and_b32_e32 v89, 0xffff0000, v95
	v_max_f32_e32 v88, v88, v88
	v_max_f32_e32 v89, v89, v89
	v_max_f32_e32 v88, 0xda24260, v88
	v_max_f32_e32 v89, 0xda24260, v89
	v_pk_mul_f32 v[88:89], v[88:89], v[90:91]
	v_pk_mul_f32 v[48:49], v[100:101], v[48:49]
	v_pk_mul_f32 v[22:23], v[88:89], v[22:23]
	v_lshlrev_b32_e32 v88, 16, v80
	v_and_b32_e32 v80, 0xffff0000, v80
	v_max_f32_e32 v80, v80, v80
	v_max_f32_e32 v89, 0xda24260, v80
	v_lshlrev_b32_e32 v80, 16, v84
	v_and_b32_e32 v84, 0xffff0000, v84
	v_max_f32_e32 v84, v84, v84
	v_max_f32_e32 v84, 0xda24260, v84
	v_cndmask_b32_e64 v84, v84, 1.0, s[6:7]
	v_rcp_f32_e32 v91, v84
	v_lshlrev_b32_e32 v84, 16, v85
	v_and_b32_e32 v85, 0xffff0000, v85
	v_max_f32_e32 v84, v84, v84
	v_max_f32_e32 v85, v85, v85
	v_max_f32_e32 v80, v80, v80
	v_max_f32_e32 v84, 0xda24260, v84
	v_max_f32_e32 v85, 0xda24260, v85
	v_max_f32_e32 v80, 0xda24260, v80
	v_cndmask_b32_e64 v84, v84, 1.0, s[6:7]
	v_cndmask_b32_e64 v85, v85, 1.0, s[6:7]
	v_cndmask_b32_e64 v80, v80, 1.0, s[6:7]
	v_rcp_f32_e32 v84, v84
	v_rcp_f32_e32 v85, v85
	v_rcp_f32_e32 v90, v80
	v_lshlrev_b32_e32 v80, 16, v81
	v_and_b32_e32 v81, 0xffff0000, v81
	v_max_f32_e32 v80, v80, v80
	v_max_f32_e32 v81, v81, v81
	v_max_f32_e32 v80, 0xda24260, v80
	v_max_f32_e32 v81, 0xda24260, v81
	v_pk_mul_f32 v[80:81], v[80:81], v[84:85]
	v_and_b32_e32 v84, 0xffff0000, v86
	v_pk_mul_f32 v[26:27], v[80:81], v[26:27]
	v_lshlrev_b32_e32 v80, 16, v82
	v_and_b32_e32 v81, 0xffff0000, v82
	v_lshlrev_b32_e32 v82, 16, v86
	v_max_f32_e32 v82, v82, v82
	v_max_f32_e32 v84, v84, v84
	v_max_f32_e32 v82, 0xda24260, v82
	v_max_f32_e32 v84, 0xda24260, v84
	v_cndmask_b32_e64 v82, v82, 1.0, s[6:7]
	v_cndmask_b32_e64 v85, v84, 1.0, s[6:7]
	v_rcp_f32_e32 v84, v82
	v_rcp_f32_e32 v85, v85
	v_max_f32_e32 v80, v80, v80
	v_max_f32_e32 v81, v81, v81
	v_max_f32_e32 v80, 0xda24260, v80
	v_max_f32_e32 v81, 0xda24260, v81
	v_pk_mul_f32 v[80:81], v[80:81], v[84:85]
	v_lshlrev_b32_e32 v82, 16, v87
	v_pk_mul_f32 v[28:29], v[80:81], v[28:29]
	v_lshlrev_b32_e32 v80, 16, v83
	v_and_b32_e32 v81, 0xffff0000, v83
	v_and_b32_e32 v83, 0xffff0000, v87
	v_max_f32_e32 v82, v82, v82
	v_max_f32_e32 v83, v83, v83
	v_max_f32_e32 v82, 0xda24260, v82
	v_max_f32_e32 v83, 0xda24260, v83
	v_cndmask_b32_e64 v82, v82, 1.0, s[6:7]
	v_cndmask_b32_e64 v83, v83, 1.0, s[6:7]
	v_rcp_f32_e32 v82, v82
	v_rcp_f32_e32 v83, v83
	v_max_f32_e32 v80, v80, v80
	v_max_f32_e32 v81, v81, v81
	v_max_f32_e32 v80, 0xda24260, v80
	v_max_f32_e32 v81, 0xda24260, v81
	v_pk_mul_f32 v[80:81], v[80:81], v[82:83]
	v_max_f32_e32 v88, v88, v88
	v_pk_mul_f32 v[30:31], v[80:81], v[30:31]
	v_lshlrev_b32_e32 v80, 16, v68
	v_and_b32_e32 v68, 0xffff0000, v68
	v_max_f32_e32 v68, v68, v68
	v_max_f32_e32 v81, 0xda24260, v68
; DI float bflo(unsigned v) { return __uint_as_float(v << 16); }
; DI float bfhi(unsigned v) { return __uint_as_float(v & 0xffff0000u); }
; template <int MASK>
; __global__ void __launch_bounds__(256, 2) fwd_megakernel_t(Params p) {
;     ...
;           const u16* gn = gbuf + ((size_t)((((br * 128 + mt) * 16 + nt) * 4 + wave) * 64 + lane)) * 64;
;           const u16* gd = gbuf + ((size_t)(((((br < 2 ? br + 1 : 2) * 128 + mt) * 16 + nt) * 4 + wave) * 64 + lane)) * 64;
; #pragma unroll
;           for (int i = 0; i < 2; i++)
; #pragma unroll
;             for (int j = 0; j < 2; j++) {
;               const uint4 n0v = *(const uint4*)(gn + (i * 2 + j) * 16), n1v = *(const uint4*)(gn + (i * 2 + j) * 16 + 8);
;               const uint4 d0v = *(const uint4*)(gd + (i * 2 + j) * 16), d1v = *(const uint4*)(gd + (i * 2 + j) * 16 + 8);
;               const unsigned nw[8] = {n0v.x, n0v.y, n0v.z, n0v.w, n1v.x, n1v.y, n1v.z, n1v.w};
;               const unsigned dw[8] = {d0v.x, d0v.y, d0v.z, d0v.w, d1v.x, d1v.y, d1v.z, d1v.w};
; #pragma unroll
;               for (int q = 0; q < 8; q++) {
;                 const float na = fmaxf(bflo(nw[q]), 1e-30f), nb = fmaxf(bfhi(nw[q]), 1e-30f);
;                 const float da = (br < 2) ? fmaxf(bflo(dw[q]), 1e-30f) : 1.f, db = (br < 2) ? fmaxf(bfhi(dw[q]), 1e-30f) : 1.f;
;                 acc[i][j][2 * q] *= na * __builtin_amdgcn_rcpf(da);
;                 acc[i][j][2 * q + 1] *= nb * __builtin_amdgcn_rcpf(db);
;               }
;             }
	v_lshlrev_b32_e32 v68, 16, v76
	v_and_b32_e32 v76, 0xffff0000, v76
	v_max_f32_e32 v76, v76, v76
	v_max_f32_e32 v76, 0xda24260, v76
	v_cndmask_b32_e64 v76, v76, 1.0, s[6:7]
	v_rcp_f32_e32 v83, v76
	v_lshlrev_b32_e32 v76, 16, v77
	v_and_b32_e32 v77, 0xffff0000, v77
	v_max_f32_e32 v76, v76, v76
	v_max_f32_e32 v77, v77, v77
	v_max_f32_e32 v68, v68, v68
	v_max_f32_e32 v76, 0xda24260, v76
	v_max_f32_e32 v77, 0xda24260, v77
	v_max_f32_e32 v68, 0xda24260, v68
	v_cndmask_b32_e64 v76, v76, 1.0, s[6:7]
	v_cndmask_b32_e64 v77, v77, 1.0, s[6:7]
	v_cndmask_b32_e64 v68, v68, 1.0, s[6:7]
	v_rcp_f32_e32 v76, v76
	v_rcp_f32_e32 v77, v77
	v_rcp_f32_e32 v82, v68
	v_lshlrev_b32_e32 v68, 16, v69
	v_and_b32_e32 v69, 0xffff0000, v69
	v_max_f32_e32 v68, v68, v68
	v_max_f32_e32 v69, v69, v69
	v_max_f32_e32 v68, 0xda24260, v68
	v_max_f32_e32 v69, 0xda24260, v69
	v_pk_mul_f32 v[68:69], v[68:69], v[76:77]
	v_and_b32_e32 v76, 0xffff0000, v78
	v_pk_mul_f32 v[2:3], v[68:69], v[2:3]
	v_lshlrev_b32_e32 v68, 16, v70
	v_and_b32_e32 v69, 0xffff0000, v70
	v_lshlrev_b32_e32 v70, 16, v78
	v_max_f32_e32 v70, v70, v70
	v_max_f32_e32 v76, v76, v76
	v_max_f32_e32 v70, 0xda24260, v70
	v_max_f32_e32 v76, 0xda24260, v76
	v_cndmask_b32_e64 v70, v70, 1.0, s[6:7]
	v_cndmask_b32_e64 v77, v76, 1.0, s[6:7]
	v_rcp_f32_e32 v76, v70
	v_rcp_f32_e32 v77, v77
	v_max_f32_e32 v68, v68, v68
	v_max_f32_e32 v69, v69, v69
	v_max_f32_e32 v68, 0xda24260, v68
	v_max_f32_e32 v69, 0xda24260, v69
	v_pk_mul_f32 v[68:69], v[68:69], v[76:77]
	v_lshlrev_b32_e32 v70, 16, v79
	v_pk_mul_f32 v[4:5], v[68:69], v[4:5]
	v_lshlrev_b32_e32 v68, 16, v71
	v_and_b32_e32 v69, 0xffff0000, v71
	v_and_b32_e32 v71, 0xffff0000, v79
	v_max_f32_e32 v70, v70, v70
	v_max_f32_e32 v71, v71, v71
	v_max_f32_e32 v70, 0xda24260, v70
	v_max_f32_e32 v71, 0xda24260, v71
	v_cndmask_b32_e64 v70, v70, 1.0, s[6:7]
	v_cndmask_b32_e64 v71, v71, 1.0, s[6:7]
	v_rcp_f32_e32 v70, v70
	v_rcp_f32_e32 v71, v71
	v_max_f32_e32 v68, v68, v68
	v_max_f32_e32 v69, v69, v69
	v_max_f32_e32 v68, 0xda24260, v68
	v_max_f32_e32 v69, 0xda24260, v69
	v_pk_mul_f32 v[68:69], v[68:69], v[70:71]
	v_and_b32_e32 v70, 0xffff0000, v72
	v_pk_mul_f32 v[6:7], v[68:69], v[6:7]
	v_lshlrev_b32_e32 v68, 16, v64
	v_and_b32_e32 v64, 0xffff0000, v64
	v_max_f32_e32 v64, v64, v64
	v_max_f32_e32 v69, 0xda24260, v64
	v_lshlrev_b32_e32 v64, 16, v72
	v_max_f32_e32 v64, v64, v64
	v_max_f32_e32 v70, v70, v70
	v_max_f32_e32 v64, 0xda24260, v64
	v_max_f32_e32 v70, 0xda24260, v70
	v_cndmask_b32_e64 v64, v64, 1.0, s[6:7]
	v_cndmask_b32_e64 v71, v70, 1.0, s[6:7]
	v_rcp_f32_e32 v70, v64
	v_rcp_f32_e32 v71, v71
	v_max_f32_e32 v68, v68, v68
	v_max_f32_e32 v68, 0xda24260, v68
	v_lshlrev_b32_e32 v64, 16, v65
	v_pk_mul_f32 v[68:69], v[68:69], v[70:71]
	v_and_b32_e32 v65, 0xffff0000, v65
	v_pk_mul_f32 v[8:9], v[68:69], v[8:9]
	v_lshlrev_b32_e32 v68, 16, v73
	v_and_b32_e32 v69, 0xffff0000, v73
	v_max_f32_e32 v68, v68, v68
	v_max_f32_e32 v69, v69, v69
	v_max_f32_e32 v68, 0xda24260, v68
	v_max_f32_e32 v69, 0xda24260, v69
	v_cndmask_b32_e64 v68, v68, 1.0, s[6:7]
	v_cndmask_b32_e64 v69, v69, 1.0, s[6:7]
	v_rcp_f32_e32 v68, v68
	v_rcp_f32_e32 v69, v69
	v_max_f32_e32 v64, v64, v64
	v_max_f32_e32 v65, v65, v65
	v_max_f32_e32 v64, 0xda24260, v64
	v_max_f32_e32 v65, 0xda24260, v65
	v_pk_mul_f32 v[64:65], v[64:65], v[68:69]
	v_and_b32_e32 v68, 0xffff0000, v74
	v_pk_mul_f32 v[10:11], v[64:65], v[10:11]
	v_lshlrev_b32_e32 v64, 16, v66
	v_and_b32_e32 v65, 0xffff0000, v66
	v_lshlrev_b32_e32 v66, 16, v74
	v_max_f32_e32 v66, v66, v66
	v_max_f32_e32 v68, v68, v68
	v_max_f32_e32 v66, 0xda24260, v66
	v_max_f32_e32 v68, 0xda24260, v68
	v_cndmask_b32_e64 v66, v66, 1.0, s[6:7]
	v_cndmask_b32_e64 v69, v68, 1.0, s[6:7]
	v_rcp_f32_e32 v68, v66
	v_rcp_f32_e32 v69, v69
	v_max_f32_e32 v64, v64, v64
	v_max_f32_e32 v65, v65, v65
	v_max_f32_e32 v64, 0xda24260, v64
	v_max_f32_e32 v65, 0xda24260, v65
	v_pk_mul_f32 v[64:65], v[64:65], v[68:69]
	v_lshlrev_b32_e32 v66, 16, v75
	v_pk_mul_f32 v[12:13], v[64:65], v[12:13]
	v_lshlrev_b32_e32 v64, 16, v67
	v_and_b32_e32 v65, 0xffff0000, v67
	v_and_b32_e32 v67, 0xffff0000, v75
	v_max_f32_e32 v66, v66, v66
	v_max_f32_e32 v67, v67, v67
	v_max_f32_e32 v66, 0xda24260, v66
	v_max_f32_e32 v67, 0xda24260, v67
	v_cndmask_b32_e64 v66, v66, 1.0, s[6:7]
	v_cndmask_b32_e64 v67, v67, 1.0, s[6:7]
	v_rcp_f32_e32 v66, v66
	v_rcp_f32_e32 v67, v67
	v_max_f32_e32 v80, v80, v80
	v_max_f32_e32 v64, v64, v64
	v_max_f32_e32 v65, v65, v65
	v_max_f32_e32 v88, 0xda24260, v88
	v_max_f32_e32 v80, 0xda24260, v80
	v_max_f32_e32 v64, 0xda24260, v64
	v_max_f32_e32 v65, 0xda24260, v65
	v_pk_mul_f32 v[88:89], v[88:89], v[90:91]
	v_pk_mul_f32 v[80:81], v[80:81], v[82:83]
	v_pk_mul_f32 v[64:65], v[64:65], v[66:67]
	v_pk_mul_f32 v[16:17], v[96:97], v[16:17]
	v_pk_mul_f32 v[24:25], v[88:89], v[24:25]
	v_pk_mul_f32 v[0:1], v[80:81], v[0:1]
	v_pk_mul_f32 v[14:15], v[64:65], v[14:15]
	s_cbranch_scc1 .LBB0_411

; template <int MASK>
; __global__ void __launch_bounds__(256, 2) fwd_megakernel_t(Params p) {
;     ...
;             if (n0 >= C_GATE) {
;               const int br = (n0 - C_GATE) >> 11, ntg = ((n0 - C_GATE) & 2047) >> 7;
;               u16* gdst = gbuf + ((size_t)((((br * 128 + mt) * 16 + ntg) * 4 + wave) * 64 + lane)) * 64 + (i * 2 + j) * 16;
;               unsigned gw[8];
; #pragma unroll
;               for (int r = 0; r < 16; r += 2)
;                 gw[r >> 1] = pack2(1.f / (1.f + __expf(-acc[i][j][r] * rv[r])), 1.f / (1.f + __expf(-acc[i][j][r + 1] * rv[r + 1])));
;               *(uint4*)(gdst) = make_uint4(gw[0], gw[1], gw[2], gw[3]);
;               *(uint4*)(gdst + 8) = make_uint4(gw[4], gw[5], gw[6], gw[7]);
.LBB0_751:
	s_add_i32 s7, s6, 0xffffed80
	s_bfe_u32 s22, s7, 0x40007
	s_lshl_b32 s23, s24, 4
	s_and_b32 s7, s7, 0xfff800
	s_add_i32 s7, s7, s23
	s_or_b32 s7, s7, s22
	v_lshl_add_u32 v80, s7, 8, v152
	v_ashrrev_i32_e32 v81, 31, v80
	v_lshlrev_b64 v[80:81], 7, v[80:81]
	s_andn2_b64 vcc, exec, s[18:19]
	v_lshl_add_u64 v[80:81], s[86:87], 0, v[80:81]
	v_and_b32_e32 v252, 63, v152
	v_mul_u32_u24_e32 v252, 0x70, v252
	v_sub_u32_e32 v252, 0x1000, v252
	v_ashrrev_i32_e32 v253, 31, v252
	v_lshl_add_u64 v[80:81], v[80:81], 0, v[252:253]
	s_cbranch_vccnz .LBB0_753
	s_waitcnt vmcnt(3)
	v_mul_f32_e64 v48, v76, -v48
	v_mul_f32_e32 v48, 0x3fb8aa3b, v48
	v_exp_f32_e32 v48, v48
	v_mul_f32_e64 v49, v77, -v49
	v_mul_f32_e32 v49, 0x3fb8aa3b, v49
	v_exp_f32_e32 v49, v49
	v_add_f32_e32 v48, 1.0, v48
	v_div_scale_f32 v83, s[18:19], v48, v48, 1.0
	v_rcp_f32_e32 v87, v83
	v_add_f32_e32 v49, 1.0, v49
	v_mul_f32_e64 v50, v78, -v50
	v_mul_f32_e32 v50, 0x3fb8aa3b, v50
	v_fma_f32 v102, -v83, v87, 1.0
	v_fmac_f32_e32 v87, v102, v87
	v_div_scale_f32 v102, vcc, 1.0, v48, 1.0
	v_mul_f32_e32 v103, v102, v87
	v_fma_f32 v104, -v83, v103, v102
	v_fmac_f32_e32 v103, v104, v87
	v_fma_f32 v83, -v83, v103, v102
	v_div_fmas_f32 v83, v83, v87, v103
	v_div_fixup_f32 v48, v83, v48, 1.0
	v_div_scale_f32 v83, s[18:19], v49, v49, 1.0
	v_rcp_f32_e32 v87, v83
	v_exp_f32_e32 v50, v50
	v_mul_f32_e64 v51, v79, -v51
	v_mul_f32_e32 v51, 0x3fb8aa3b, v51
	v_fma_f32 v102, -v83, v87, 1.0
	v_fmac_f32_e32 v87, v102, v87
	v_div_scale_f32 v102, vcc, 1.0, v49, 1.0
	v_mul_f32_e32 v103, v102, v87
	v_fma_f32 v104, -v83, v103, v102
	v_fmac_f32_e32 v103, v104, v87
	v_fma_f32 v83, -v83, v103, v102
	v_div_fmas_f32 v83, v83, v87, v103
	v_add_f32_e32 v50, 1.0, v50
	v_div_fixup_f32 v49, v83, v49, 1.0
	v_div_scale_f32 v83, s[18:19], v50, v50, 1.0
	v_rcp_f32_e32 v87, v83
	v_exp_f32_e32 v51, v51
	s_waitcnt vmcnt(2)
	v_mul_f32_e64 v52, v72, -v52
	v_mul_f32_e32 v52, 0x3fb8aa3b, v52
	v_fma_f32 v102, -v83, v87, 1.0
	v_fmac_f32_e32 v87, v102, v87
	v_div_scale_f32 v102, vcc, 1.0, v50, 1.0
	v_mul_f32_e32 v103, v102, v87
	v_fma_f32 v104, -v83, v103, v102
	v_fmac_f32_e32 v103, v104, v87
	v_fma_f32 v83, -v83, v103, v102
	v_div_fmas_f32 v83, v83, v87, v103
	v_add_f32_e32 v51, 1.0, v51
	v_div_fixup_f32 v50, v83, v50, 1.0
	v_div_scale_f32 v83, s[18:19], v51, v51, 1.0
	v_rcp_f32_e32 v87, v83
	v_exp_f32_e32 v52, v52
	v_mul_f32_e64 v53, v73, -v53
	v_mul_f32_e32 v53, 0x3fb8aa3b, v53
	v_fma_f32 v102, -v83, v87, 1.0
	v_fmac_f32_e32 v87, v102, v87
	v_div_scale_f32 v102, vcc, 1.0, v51, 1.0
	v_mul_f32_e32 v103, v102, v87
	v_fma_f32 v104, -v83, v103, v102
	v_fmac_f32_e32 v103, v104, v87
	v_fma_f32 v83, -v83, v103, v102
	v_div_fmas_f32 v83, v83, v87, v103
	v_add_f32_e32 v52, 1.0, v52
	v_div_fixup_f32 v51, v83, v51, 1.0
	v_div_scale_f32 v83, s[18:19], v52, v52, 1.0
	v_rcp_f32_e32 v87, v83
	v_exp_f32_e32 v53, v53
	v_mul_f32_e64 v54, v74, -v54
	v_mul_f32_e32 v54, 0x3fb8aa3b, v54
	v_fma_f32 v102, -v83, v87, 1.0
	v_fmac_f32_e32 v87, v102, v87
	v_div_scale_f32 v102, vcc, 1.0, v52, 1.0
	v_mul_f32_e32 v103, v102, v87
	v_fma_f32 v104, -v83, v103, v102
	v_fmac_f32_e32 v103, v104, v87
	v_fma_f32 v83, -v83, v103, v102
	v_div_fmas_f32 v83, v83, v87, v103
	v_add_f32_e32 v53, 1.0, v53
	v_div_fixup_f32 v52, v83, v52, 1.0
	v_div_scale_f32 v83, s[18:19], v53, v53, 1.0
	v_rcp_f32_e32 v87, v83
	v_exp_f32_e32 v54, v54
	v_mul_f32_e64 v55, v75, -v55
	v_mul_f32_e32 v55, 0x3fb8aa3b, v55
	v_fma_f32 v102, -v83, v87, 1.0
	v_fmac_f32_e32 v87, v102, v87
	v_div_scale_f32 v102, vcc, 1.0, v53, 1.0
	v_mul_f32_e32 v103, v102, v87
	v_fma_f32 v104, -v83, v103, v102
	v_fmac_f32_e32 v103, v104, v87
	v_fma_f32 v83, -v83, v103, v102
	v_div_fmas_f32 v83, v83, v87, v103
	v_add_f32_e32 v54, 1.0, v54
	v_div_fixup_f32 v53, v83, v53, 1.0
	v_div_scale_f32 v83, s[18:19], v54, v54, 1.0
	v_rcp_f32_e32 v87, v83
	v_exp_f32_e32 v55, v55
	s_waitcnt vmcnt(1)
; template <int MASK>
; __global__ void __launch_bounds__(256, 2) fwd_megakernel_t(Params p) {
;     ...
;             if (n0 >= C_GATE) {
;               const int br = (n0 - C_GATE) >> 11, ntg = ((n0 - C_GATE) & 2047) >> 7;
;               u16* gdst = gbuf + ((size_t)((((br * 128 + mt) * 16 + ntg) * 4 + wave) * 64 + lane)) * 64 + (i * 2 + j) * 16;
;               unsigned gw[8];
; #pragma unroll
;               for (int r = 0; r < 16; r += 2)
;                 gw[r >> 1] = pack2(1.f / (1.f + __expf(-acc[i][j][r] * rv[r])), 1.f / (1.f + __expf(-acc[i][j][r + 1] * rv[r + 1])));
;               *(uint4*)(gdst) = make_uint4(gw[0], gw[1], gw[2], gw[3]);
;               *(uint4*)(gdst + 8) = make_uint4(gw[4], gw[5], gw[6], gw[7]);
	v_mul_f32_e64 v56, v68, -v56
	v_mul_f32_e32 v56, 0x3fb8aa3b, v56
	v_fma_f32 v102, -v83, v87, 1.0
	v_fmac_f32_e32 v87, v102, v87
	v_div_scale_f32 v102, vcc, 1.0, v54, 1.0
	v_mul_f32_e32 v103, v102, v87
	v_fma_f32 v104, -v83, v103, v102
	v_fmac_f32_e32 v103, v104, v87
	v_fma_f32 v83, -v83, v103, v102
	v_div_fmas_f32 v83, v83, v87, v103
	v_add_f32_e32 v55, 1.0, v55
	v_div_fixup_f32 v54, v83, v54, 1.0
	v_div_scale_f32 v83, s[18:19], v55, v55, 1.0
	v_rcp_f32_e32 v87, v83
	v_exp_f32_e32 v56, v56
	v_mul_f32_e64 v57, v69, -v57
	v_mul_f32_e32 v57, 0x3fb8aa3b, v57
	v_fma_f32 v102, -v83, v87, 1.0
	v_fmac_f32_e32 v87, v102, v87
	v_div_scale_f32 v102, vcc, 1.0, v55, 1.0
	v_mul_f32_e32 v103, v102, v87
	v_fma_f32 v104, -v83, v103, v102
	v_fmac_f32_e32 v103, v104, v87
	v_fma_f32 v83, -v83, v103, v102
	v_div_fmas_f32 v83, v83, v87, v103
	v_add_f32_e32 v56, 1.0, v56
	v_div_fixup_f32 v55, v83, v55, 1.0
	v_div_scale_f32 v83, s[18:19], v56, v56, 1.0
	v_rcp_f32_e32 v87, v83
	v_exp_f32_e32 v57, v57
	v_mul_f32_e64 v58, v70, -v58
	v_mul_f32_e32 v58, 0x3fb8aa3b, v58
	v_fma_f32 v102, -v83, v87, 1.0
	v_fmac_f32_e32 v87, v102, v87
	v_div_scale_f32 v102, vcc, 1.0, v56, 1.0
	v_mul_f32_e32 v103, v102, v87
	v_fma_f32 v104, -v83, v103, v102
	v_fmac_f32_e32 v103, v104, v87
	v_fma_f32 v83, -v83, v103, v102
	v_div_fmas_f32 v83, v83, v87, v103
	v_add_f32_e32 v57, 1.0, v57
	v_div_fixup_f32 v56, v83, v56, 1.0
	v_div_scale_f32 v83, s[18:19], v57, v57, 1.0
	v_rcp_f32_e32 v87, v83
	v_exp_f32_e32 v58, v58
	v_mul_f32_e64 v59, v71, -v59
	v_mul_f32_e32 v59, 0x3fb8aa3b, v59
	v_fma_f32 v102, -v83, v87, 1.0
	v_fmac_f32_e32 v87, v102, v87
	v_div_scale_f32 v102, vcc, 1.0, v57, 1.0
	v_mul_f32_e32 v103, v102, v87
	v_fma_f32 v104, -v83, v103, v102
	v_fmac_f32_e32 v103, v104, v87
	v_fma_f32 v83, -v83, v103, v102
	v_div_fmas_f32 v83, v83, v87, v103
	v_add_f32_e32 v58, 1.0, v58
	v_div_fixup_f32 v57, v83, v57, 1.0
	v_div_scale_f32 v83, s[18:19], v58, v58, 1.0
	v_rcp_f32_e32 v87, v83
	v_exp_f32_e32 v59, v59
	s_waitcnt vmcnt(0)
	v_mul_f32_e64 v60, v64, -v60
	v_mul_f32_e32 v60, 0x3fb8aa3b, v60
	v_fma_f32 v102, -v83, v87, 1.0
	v_fmac_f32_e32 v87, v102, v87
	v_div_scale_f32 v102, vcc, 1.0, v58, 1.0
	v_mul_f32_e32 v103, v102, v87
	v_fma_f32 v104, -v83, v103, v102
	v_fmac_f32_e32 v103, v104, v87
	v_fma_f32 v83, -v83, v103, v102
	v_div_fmas_f32 v83, v83, v87, v103
	v_add_f32_e32 v59, 1.0, v59
	v_div_fixup_f32 v58, v83, v58, 1.0
	v_div_scale_f32 v83, s[18:19], v59, v59, 1.0
	v_rcp_f32_e32 v87, v83
	v_exp_f32_e32 v60, v60
	v_mul_f32_e64 v61, v65, -v61
	v_mul_f32_e32 v61, 0x3fb8aa3b, v61
	v_fma_f32 v102, -v83, v87, 1.0
	v_fmac_f32_e32 v87, v102, v87
	v_div_scale_f32 v102, vcc, 1.0, v59, 1.0
	v_mul_f32_e32 v103, v102, v87
	v_fma_f32 v104, -v83, v103, v102
	v_fmac_f32_e32 v103, v104, v87
	v_fma_f32 v83, -v83, v103, v102
	v_div_fmas_f32 v83, v83, v87, v103
	v_add_f32_e32 v60, 1.0, v60
	v_div_fixup_f32 v59, v83, v59, 1.0
	v_div_scale_f32 v83, s[18:19], v60, v60, 1.0
	v_rcp_f32_e32 v87, v83
	v_exp_f32_e32 v61, v61
	v_mul_f32_e64 v62, v66, -v62
	v_mul_f32_e32 v62, 0x3fb8aa3b, v62
	v_fma_f32 v102, -v83, v87, 1.0
	v_fmac_f32_e32 v87, v102, v87
	v_div_scale_f32 v102, vcc, 1.0, v60, 1.0
	v_mul_f32_e32 v103, v102, v87
	v_fma_f32 v104, -v83, v103, v102
	v_fmac_f32_e32 v103, v104, v87
	v_fma_f32 v83, -v83, v103, v102
	v_div_fmas_f32 v83, v83, v87, v103
	v_add_f32_e32 v61, 1.0, v61
	v_div_fixup_f32 v60, v83, v60, 1.0
	v_div_scale_f32 v83, s[18:19], v61, v61, 1.0
	v_rcp_f32_e32 v87, v83
	v_exp_f32_e32 v62, v62
	v_mul_f32_e64 v63, v67, -v63
	v_mul_f32_e32 v63, 0x3fb8aa3b, v63
	v_fma_f32 v102, -v83, v87, 1.0
	v_fmac_f32_e32 v87, v102, v87
	v_div_scale_f32 v102, vcc, 1.0, v61, 1.0
	v_mul_f32_e32 v103, v102, v87
	v_fma_f32 v104, -v83, v103, v102
	v_fmac_f32_e32 v103, v104, v87
	v_fma_f32 v83, -v83, v103, v102
	v_div_fmas_f32 v83, v83, v87, v103
	v_add_f32_e32 v62, 1.0, v62
	v_div_fixup_f32 v61, v83, v61, 1.0
	v_div_scale_f32 v83, s[18:19], v62, v62, 1.0
	v_rcp_f32_e32 v87, v83
	v_exp_f32_e32 v63, v63
	v_cvt_pk_bf16_f32 v55, v54, v55
	v_cvt_pk_bf16_f32 v54, v52, v53
	v_fma_f32 v102, -v83, v87, 1.0
	v_fmac_f32_e32 v87, v102, v87
	v_div_scale_f32 v102, vcc, 1.0, v62, 1.0
	v_mul_f32_e32 v103, v102, v87
	v_fma_f32 v104, -v83, v103, v102
	v_fmac_f32_e32 v103, v104, v87
	v_fma_f32 v83, -v83, v103, v102
	v_div_fmas_f32 v83, v83, v87, v103
	v_add_f32_e32 v63, 1.0, v63
	v_div_fixup_f32 v62, v83, v62, 1.0
	v_div_scale_f32 v83, s[18:19], v63, v63, 1.0
	v_rcp_f32_e32 v87, v83
	v_cvt_pk_bf16_f32 v53, v50, v51
	v_cvt_pk_bf16_f32 v52, v48, v49
	v_cvt_pk_bf16_f32 v50, v60, v61
	v_fma_f32 v102, -v83, v87, 1.0
	v_fmac_f32_e32 v87, v102, v87
	v_div_scale_f32 v102, vcc, 1.0, v63, 1.0
	v_mul_f32_e32 v103, v102, v87
	v_fma_f32 v104, -v83, v103, v102
	v_fmac_f32_e32 v103, v104, v87
	v_fma_f32 v83, -v83, v103, v102
	v_div_fmas_f32 v83, v83, v87, v103
	v_div_fixup_f32 v63, v83, v63, 1.0
	v_cvt_pk_bf16_f32 v51, v62, v63
	v_cvt_pk_bf16_f32 v49, v58, v59
	v_cvt_pk_bf16_f32 v48, v56, v57
	global_store_dwordx4 v[80:81], v[52:55], off offset:-4096
	global_store_dwordx4 v[80:81], v[48:51], off offset:-3072

; template <int MASK>
; __global__ void __launch_bounds__(256, 2) fwd_megakernel_t(Params p) {
;     ...
;             if (n0 >= C_GATE) {
;               const int br = (n0 - C_GATE) >> 11, ntg = ((n0 - C_GATE) & 2047) >> 7;
;               u16* gdst = gbuf + ((size_t)((((br * 128 + mt) * 16 + ntg) * 4 + wave) * 64 + lane)) * 64 + (i * 2 + j) * 16;
;               unsigned gw[8];
; #pragma unroll
;               for (int r = 0; r < 16; r += 2)
;                 gw[r >> 1] = pack2(1.f / (1.f + __expf(-acc[i][j][r] * rv[r])), 1.f / (1.f + __expf(-acc[i][j][r + 1] * rv[r + 1])));
;               *(uint4*)(gdst) = make_uint4(gw[0], gw[1], gw[2], gw[3]);
;               *(uint4*)(gdst + 8) = make_uint4(gw[4], gw[5], gw[6], gw[7]);
.LBB0_764:
	s_andn2_b64 vcc, exec, s[16:17]
	s_cbranch_vccnz .LBB0_766
	s_waitcnt vmcnt(3)
	v_mul_f32_e64 v32, v76, -v32
	v_mul_f32_e32 v32, 0x3fb8aa3b, v32
	v_exp_f32_e32 v32, v32
	v_mul_f32_e64 v33, v77, -v33
	v_mul_f32_e32 v33, 0x3fb8aa3b, v33
	v_exp_f32_e32 v33, v33
	v_add_f32_e32 v32, 1.0, v32
	v_div_scale_f32 v49, s[16:17], v32, v32, 1.0
	v_rcp_f32_e32 v50, v49
	v_add_f32_e32 v33, 1.0, v33
	v_mul_f32_e64 v34, v78, -v34
	v_mul_f32_e32 v34, 0x3fb8aa3b, v34
	v_fma_f32 v51, -v49, v50, 1.0
	v_fmac_f32_e32 v50, v51, v50
	v_div_scale_f32 v51, vcc, 1.0, v32, 1.0
	v_mul_f32_e32 v52, v51, v50
	v_fma_f32 v53, -v49, v52, v51
	v_fmac_f32_e32 v52, v53, v50
	v_fma_f32 v49, -v49, v52, v51
	v_div_fmas_f32 v49, v49, v50, v52
	v_div_fixup_f32 v32, v49, v32, 1.0
	v_div_scale_f32 v49, s[16:17], v33, v33, 1.0
	v_rcp_f32_e32 v50, v49
	v_exp_f32_e32 v34, v34
	v_mul_f32_e64 v35, v79, -v35
	v_mul_f32_e32 v35, 0x3fb8aa3b, v35
	v_fma_f32 v51, -v49, v50, 1.0
	v_fmac_f32_e32 v50, v51, v50
	v_div_scale_f32 v51, vcc, 1.0, v33, 1.0
	v_mul_f32_e32 v52, v51, v50
	v_fma_f32 v53, -v49, v52, v51
	v_fmac_f32_e32 v52, v53, v50
	v_fma_f32 v49, -v49, v52, v51
	v_div_fmas_f32 v49, v49, v50, v52
	v_add_f32_e32 v34, 1.0, v34
	v_div_fixup_f32 v33, v49, v33, 1.0
	v_div_scale_f32 v49, s[16:17], v34, v34, 1.0
	v_rcp_f32_e32 v50, v49
	v_exp_f32_e32 v35, v35
	s_waitcnt vmcnt(2)
	v_mul_f32_e64 v36, v72, -v36
	v_mul_f32_e32 v36, 0x3fb8aa3b, v36
	v_fma_f32 v51, -v49, v50, 1.0
	v_fmac_f32_e32 v50, v51, v50
	v_div_scale_f32 v51, vcc, 1.0, v34, 1.0
	v_mul_f32_e32 v52, v51, v50
	v_fma_f32 v53, -v49, v52, v51
	v_fmac_f32_e32 v52, v53, v50
	v_fma_f32 v49, -v49, v52, v51
	v_div_fmas_f32 v49, v49, v50, v52
	v_add_f32_e32 v35, 1.0, v35
	v_div_fixup_f32 v34, v49, v34, 1.0
	v_div_scale_f32 v49, s[16:17], v35, v35, 1.0
	v_rcp_f32_e32 v50, v49
	v_exp_f32_e32 v36, v36
	v_mul_f32_e64 v37, v73, -v37
	v_mul_f32_e32 v37, 0x3fb8aa3b, v37
	v_fma_f32 v51, -v49, v50, 1.0
	v_fmac_f32_e32 v50, v51, v50
	v_div_scale_f32 v51, vcc, 1.0, v35, 1.0
	v_mul_f32_e32 v52, v51, v50
	v_fma_f32 v53, -v49, v52, v51
	v_fmac_f32_e32 v52, v53, v50
	v_fma_f32 v49, -v49, v52, v51
	v_div_fmas_f32 v49, v49, v50, v52
	v_add_f32_e32 v36, 1.0, v36
	v_div_fixup_f32 v35, v49, v35, 1.0
	v_div_scale_f32 v49, s[16:17], v36, v36, 1.0
	v_rcp_f32_e32 v50, v49
	v_exp_f32_e32 v37, v37
	v_mul_f32_e64 v38, v74, -v38
	v_mul_f32_e32 v38, 0x3fb8aa3b, v38
	v_fma_f32 v51, -v49, v50, 1.0
	v_fmac_f32_e32 v50, v51, v50
	v_div_scale_f32 v51, vcc, 1.0, v36, 1.0
	v_mul_f32_e32 v52, v51, v50
	v_fma_f32 v53, -v49, v52, v51
	v_fmac_f32_e32 v52, v53, v50
	v_fma_f32 v49, -v49, v52, v51
	v_div_fmas_f32 v49, v49, v50, v52
	v_add_f32_e32 v37, 1.0, v37
	v_div_fixup_f32 v36, v49, v36, 1.0
	v_div_scale_f32 v49, s[16:17], v37, v37, 1.0
	v_rcp_f32_e32 v50, v49
	v_exp_f32_e32 v38, v38
	v_mul_f32_e64 v39, v75, -v39
	v_mul_f32_e32 v39, 0x3fb8aa3b, v39
	v_fma_f32 v51, -v49, v50, 1.0
	v_fmac_f32_e32 v50, v51, v50
	v_div_scale_f32 v51, vcc, 1.0, v37, 1.0
	v_mul_f32_e32 v52, v51, v50
	v_fma_f32 v53, -v49, v52, v51
	v_fmac_f32_e32 v52, v53, v50
	v_fma_f32 v49, -v49, v52, v51
	v_div_fmas_f32 v49, v49, v50, v52
	v_add_f32_e32 v38, 1.0, v38
	v_div_fixup_f32 v37, v49, v37, 1.0
	v_div_scale_f32 v49, s[16:17], v38, v38, 1.0
	v_rcp_f32_e32 v50, v49
	v_exp_f32_e32 v39, v39
	s_waitcnt vmcnt(1)
; template <int MASK>
; __global__ void __launch_bounds__(256, 2) fwd_megakernel_t(Params p) {
;     ...
;             if (n0 >= C_GATE) {
;               const int br = (n0 - C_GATE) >> 11, ntg = ((n0 - C_GATE) & 2047) >> 7;
;               u16* gdst = gbuf + ((size_t)((((br * 128 + mt) * 16 + ntg) * 4 + wave) * 64 + lane)) * 64 + (i * 2 + j) * 16;
;               unsigned gw[8];
; #pragma unroll
;               for (int r = 0; r < 16; r += 2)
;                 gw[r >> 1] = pack2(1.f / (1.f + __expf(-acc[i][j][r] * rv[r])), 1.f / (1.f + __expf(-acc[i][j][r + 1] * rv[r + 1])));
;               *(uint4*)(gdst) = make_uint4(gw[0], gw[1], gw[2], gw[3]);
;               *(uint4*)(gdst + 8) = make_uint4(gw[4], gw[5], gw[6], gw[7]);
	v_mul_f32_e64 v40, v68, -v40
	v_mul_f32_e32 v40, 0x3fb8aa3b, v40
	v_fma_f32 v51, -v49, v50, 1.0
	v_fmac_f32_e32 v50, v51, v50
	v_div_scale_f32 v51, vcc, 1.0, v38, 1.0
	v_mul_f32_e32 v52, v51, v50
	v_fma_f32 v53, -v49, v52, v51
	v_fmac_f32_e32 v52, v53, v50
	v_fma_f32 v49, -v49, v52, v51
	v_div_fmas_f32 v49, v49, v50, v52
	v_add_f32_e32 v39, 1.0, v39
	v_div_fixup_f32 v38, v49, v38, 1.0
	v_div_scale_f32 v49, s[16:17], v39, v39, 1.0
	v_rcp_f32_e32 v50, v49
	v_exp_f32_e32 v40, v40
	v_mul_f32_e64 v41, v69, -v41
	v_mul_f32_e32 v41, 0x3fb8aa3b, v41
	v_fma_f32 v51, -v49, v50, 1.0
	v_fmac_f32_e32 v50, v51, v50
	v_div_scale_f32 v51, vcc, 1.0, v39, 1.0
	v_mul_f32_e32 v52, v51, v50
	v_fma_f32 v53, -v49, v52, v51
	v_fmac_f32_e32 v52, v53, v50
	v_fma_f32 v49, -v49, v52, v51
	v_div_fmas_f32 v49, v49, v50, v52
	v_add_f32_e32 v40, 1.0, v40
	v_div_fixup_f32 v39, v49, v39, 1.0
	v_div_scale_f32 v49, s[16:17], v40, v40, 1.0
	v_rcp_f32_e32 v50, v49
	v_exp_f32_e32 v41, v41
	v_mul_f32_e64 v42, v70, -v42
	v_mul_f32_e32 v42, 0x3fb8aa3b, v42
	v_fma_f32 v51, -v49, v50, 1.0
	v_fmac_f32_e32 v50, v51, v50
	v_div_scale_f32 v51, vcc, 1.0, v40, 1.0
	v_mul_f32_e32 v52, v51, v50
	v_fma_f32 v53, -v49, v52, v51
	v_fmac_f32_e32 v52, v53, v50
	v_fma_f32 v49, -v49, v52, v51
	v_div_fmas_f32 v49, v49, v50, v52
	v_add_f32_e32 v41, 1.0, v41
	v_div_fixup_f32 v40, v49, v40, 1.0
	v_div_scale_f32 v49, s[16:17], v41, v41, 1.0
	v_rcp_f32_e32 v50, v49
	v_exp_f32_e32 v42, v42
	v_mul_f32_e64 v43, v71, -v43
	v_mul_f32_e32 v43, 0x3fb8aa3b, v43
	v_fma_f32 v51, -v49, v50, 1.0
	v_fmac_f32_e32 v50, v51, v50
	v_div_scale_f32 v51, vcc, 1.0, v41, 1.0
	v_mul_f32_e32 v52, v51, v50
	v_fma_f32 v53, -v49, v52, v51
	v_fmac_f32_e32 v52, v53, v50
	v_fma_f32 v49, -v49, v52, v51
	v_div_fmas_f32 v49, v49, v50, v52
	v_add_f32_e32 v42, 1.0, v42
	v_div_fixup_f32 v41, v49, v41, 1.0
	v_div_scale_f32 v49, s[16:17], v42, v42, 1.0
	v_rcp_f32_e32 v50, v49
	v_exp_f32_e32 v43, v43
	s_waitcnt vmcnt(0)
	v_mul_f32_e64 v44, v64, -v44
	v_mul_f32_e32 v44, 0x3fb8aa3b, v44
	v_fma_f32 v51, -v49, v50, 1.0
	v_fmac_f32_e32 v50, v51, v50
	v_div_scale_f32 v51, vcc, 1.0, v42, 1.0
	v_mul_f32_e32 v52, v51, v50
	v_fma_f32 v53, -v49, v52, v51
	v_fmac_f32_e32 v52, v53, v50
	v_fma_f32 v49, -v49, v52, v51
	v_div_fmas_f32 v49, v49, v50, v52
	v_add_f32_e32 v43, 1.0, v43
	v_div_fixup_f32 v42, v49, v42, 1.0
	v_div_scale_f32 v49, s[16:17], v43, v43, 1.0
	v_rcp_f32_e32 v50, v49
	v_exp_f32_e32 v44, v44
	v_mul_f32_e64 v45, v65, -v45
	v_mul_f32_e32 v45, 0x3fb8aa3b, v45
	v_fma_f32 v51, -v49, v50, 1.0
	v_fmac_f32_e32 v50, v51, v50
	v_div_scale_f32 v51, vcc, 1.0, v43, 1.0
	v_mul_f32_e32 v52, v51, v50
	v_fma_f32 v53, -v49, v52, v51
	v_fmac_f32_e32 v52, v53, v50
	v_fma_f32 v49, -v49, v52, v51
	v_div_fmas_f32 v49, v49, v50, v52
	v_add_f32_e32 v44, 1.0, v44
	v_div_fixup_f32 v43, v49, v43, 1.0
	v_div_scale_f32 v49, s[16:17], v44, v44, 1.0
	v_rcp_f32_e32 v50, v49
	v_exp_f32_e32 v45, v45
	v_mul_f32_e64 v46, v66, -v46
	v_mul_f32_e32 v46, 0x3fb8aa3b, v46
	v_fma_f32 v51, -v49, v50, 1.0
	v_fmac_f32_e32 v50, v51, v50
	v_div_scale_f32 v51, vcc, 1.0, v44, 1.0
	v_mul_f32_e32 v52, v51, v50
	v_fma_f32 v53, -v49, v52, v51
	v_fmac_f32_e32 v52, v53, v50
	v_fma_f32 v49, -v49, v52, v51
	v_div_fmas_f32 v49, v49, v50, v52
	v_add_f32_e32 v45, 1.0, v45
	v_div_fixup_f32 v44, v49, v44, 1.0
	v_div_scale_f32 v49, s[16:17], v45, v45, 1.0
	v_rcp_f32_e32 v50, v49
	v_exp_f32_e32 v46, v46
	v_mul_f32_e64 v47, v67, -v47
	v_mul_f32_e32 v47, 0x3fb8aa3b, v47
	v_fma_f32 v51, -v49, v50, 1.0
	v_fmac_f32_e32 v50, v51, v50
	v_div_scale_f32 v51, vcc, 1.0, v45, 1.0
	v_mul_f32_e32 v52, v51, v50
	v_fma_f32 v53, -v49, v52, v51
	v_fmac_f32_e32 v52, v53, v50
	v_fma_f32 v49, -v49, v52, v51
	v_div_fmas_f32 v49, v49, v50, v52
	v_add_f32_e32 v46, 1.0, v46
	v_div_fixup_f32 v45, v49, v45, 1.0
	v_div_scale_f32 v49, s[16:17], v46, v46, 1.0
	v_rcp_f32_e32 v50, v49
	v_exp_f32_e32 v47, v47
	v_cvt_pk_bf16_f32 v39, v38, v39
	v_cvt_pk_bf16_f32 v38, v36, v37
	v_fma_f32 v51, -v49, v50, 1.0
	v_fmac_f32_e32 v50, v51, v50
	v_div_scale_f32 v51, vcc, 1.0, v46, 1.0
	v_mul_f32_e32 v52, v51, v50
	v_fma_f32 v53, -v49, v52, v51
	v_fmac_f32_e32 v52, v53, v50
	v_fma_f32 v49, -v49, v52, v51
	v_div_fmas_f32 v49, v49, v50, v52
	v_add_f32_e32 v47, 1.0, v47
	v_div_fixup_f32 v46, v49, v46, 1.0
	v_div_scale_f32 v49, s[16:17], v47, v47, 1.0
	v_rcp_f32_e32 v50, v49
	v_cvt_pk_bf16_f32 v37, v34, v35
	v_cvt_pk_bf16_f32 v36, v32, v33
	v_cvt_pk_bf16_f32 v34, v44, v45
	v_fma_f32 v51, -v49, v50, 1.0
	v_fmac_f32_e32 v50, v51, v50
	v_div_scale_f32 v51, vcc, 1.0, v47, 1.0
	v_mul_f32_e32 v52, v51, v50
	v_fma_f32 v53, -v49, v52, v51
	v_fmac_f32_e32 v52, v53, v50
	v_fma_f32 v49, -v49, v52, v51
	v_div_fmas_f32 v49, v49, v50, v52
	v_div_fixup_f32 v47, v49, v47, 1.0
	v_cvt_pk_bf16_f32 v35, v46, v47
	v_cvt_pk_bf16_f32 v33, v42, v43
	v_cvt_pk_bf16_f32 v32, v40, v41
	global_store_dwordx4 v[80:81], v[36:39], off offset:-2048
	global_store_dwordx4 v[80:81], v[32:35], off offset:-1024

; template <int MASK>
; __global__ void __launch_bounds__(256, 2) fwd_megakernel_t(Params p) {
;     ...
;             if (n0 >= C_GATE) {
;               const int br = (n0 - C_GATE) >> 11, ntg = ((n0 - C_GATE) & 2047) >> 7;
;               u16* gdst = gbuf + ((size_t)((((br * 128 + mt) * 16 + ntg) * 4 + wave) * 64 + lane)) * 64 + (i * 2 + j) * 16;
;               unsigned gw[8];
; #pragma unroll
;               for (int r = 0; r < 16; r += 2)
;                 gw[r >> 1] = pack2(1.f / (1.f + __expf(-acc[i][j][r] * rv[r])), 1.f / (1.f + __expf(-acc[i][j][r + 1] * rv[r + 1])));
;               *(uint4*)(gdst) = make_uint4(gw[0], gw[1], gw[2], gw[3]);
;               *(uint4*)(gdst + 8) = make_uint4(gw[4], gw[5], gw[6], gw[7]);
.LBB0_770:
	s_waitcnt vmcnt(3)
	v_mul_f32_e64 v0, v44, -v0
	v_mul_f32_e32 v0, 0x3fb8aa3b, v0
	v_exp_f32_e32 v0, v0
	v_mul_f32_e64 v1, v45, -v1
	v_mul_f32_e32 v1, 0x3fb8aa3b, v1
	v_exp_f32_e32 v1, v1
	v_add_f32_e32 v0, 1.0, v0
	v_div_scale_f32 v16, s[4:5], v0, v0, 1.0
	v_rcp_f32_e32 v17, v16
	v_add_f32_e32 v1, 1.0, v1
	v_mul_f32_e64 v2, v46, -v2
	v_mul_f32_e32 v2, 0x3fb8aa3b, v2
	v_fma_f32 v18, -v16, v17, 1.0
	v_fmac_f32_e32 v17, v18, v17
	v_div_scale_f32 v18, vcc, 1.0, v0, 1.0
	v_mul_f32_e32 v19, v18, v17
	v_fma_f32 v20, -v16, v19, v18
	v_fmac_f32_e32 v19, v20, v17
	v_fma_f32 v16, -v16, v19, v18
	v_div_fmas_f32 v16, v16, v17, v19
	v_div_fixup_f32 v0, v16, v0, 1.0
	v_div_scale_f32 v16, s[4:5], v1, v1, 1.0
	v_rcp_f32_e32 v17, v16
	v_exp_f32_e32 v2, v2
	v_mul_f32_e64 v3, v47, -v3
	v_mul_f32_e32 v3, 0x3fb8aa3b, v3
	v_fma_f32 v18, -v16, v17, 1.0
	v_fmac_f32_e32 v17, v18, v17
	v_div_scale_f32 v18, vcc, 1.0, v1, 1.0
	v_mul_f32_e32 v19, v18, v17
	v_fma_f32 v20, -v16, v19, v18
	v_fmac_f32_e32 v19, v20, v17
	v_fma_f32 v16, -v16, v19, v18
	v_div_fmas_f32 v16, v16, v17, v19
	v_add_f32_e32 v2, 1.0, v2
	v_div_fixup_f32 v1, v16, v1, 1.0
	v_div_scale_f32 v16, s[4:5], v2, v2, 1.0
	v_rcp_f32_e32 v17, v16
	v_exp_f32_e32 v3, v3
	s_waitcnt vmcnt(2)
	v_mul_f32_e64 v4, v40, -v4
	v_mul_f32_e32 v4, 0x3fb8aa3b, v4
	v_fma_f32 v18, -v16, v17, 1.0
	v_fmac_f32_e32 v17, v18, v17
	v_div_scale_f32 v18, vcc, 1.0, v2, 1.0
	v_mul_f32_e32 v19, v18, v17
	v_fma_f32 v20, -v16, v19, v18
	v_fmac_f32_e32 v19, v20, v17
	v_fma_f32 v16, -v16, v19, v18
	v_div_fmas_f32 v16, v16, v17, v19
	v_add_f32_e32 v3, 1.0, v3
	v_div_fixup_f32 v2, v16, v2, 1.0
	v_div_scale_f32 v16, s[4:5], v3, v3, 1.0
	v_rcp_f32_e32 v17, v16
	v_exp_f32_e32 v4, v4
	v_mul_f32_e64 v5, v41, -v5
	v_mul_f32_e32 v5, 0x3fb8aa3b, v5
	v_fma_f32 v18, -v16, v17, 1.0
	v_fmac_f32_e32 v17, v18, v17
	v_div_scale_f32 v18, vcc, 1.0, v3, 1.0
	v_mul_f32_e32 v19, v18, v17
	v_fma_f32 v20, -v16, v19, v18
	v_fmac_f32_e32 v19, v20, v17
	v_fma_f32 v16, -v16, v19, v18
	v_div_fmas_f32 v16, v16, v17, v19
	v_add_f32_e32 v4, 1.0, v4
	v_div_fixup_f32 v3, v16, v3, 1.0
	v_div_scale_f32 v16, s[4:5], v4, v4, 1.0
	v_rcp_f32_e32 v17, v16
	v_exp_f32_e32 v5, v5
	v_mul_f32_e64 v6, v42, -v6
	v_mul_f32_e32 v6, 0x3fb8aa3b, v6
	v_fma_f32 v18, -v16, v17, 1.0
	v_fmac_f32_e32 v17, v18, v17
	v_div_scale_f32 v18, vcc, 1.0, v4, 1.0
	v_mul_f32_e32 v19, v18, v17
	v_fma_f32 v20, -v16, v19, v18
	v_fmac_f32_e32 v19, v20, v17
	v_fma_f32 v16, -v16, v19, v18
	v_div_fmas_f32 v16, v16, v17, v19
	v_add_f32_e32 v5, 1.0, v5
	v_div_fixup_f32 v4, v16, v4, 1.0
	v_div_scale_f32 v16, s[4:5], v5, v5, 1.0
	v_rcp_f32_e32 v17, v16
	v_exp_f32_e32 v6, v6
	v_mul_f32_e64 v7, v43, -v7
	v_mul_f32_e32 v7, 0x3fb8aa3b, v7
	v_fma_f32 v18, -v16, v17, 1.0
	v_fmac_f32_e32 v17, v18, v17
	v_div_scale_f32 v18, vcc, 1.0, v5, 1.0
	v_mul_f32_e32 v19, v18, v17
	v_fma_f32 v20, -v16, v19, v18
	v_fmac_f32_e32 v19, v20, v17
	v_fma_f32 v16, -v16, v19, v18
	v_div_fmas_f32 v16, v16, v17, v19
	v_add_f32_e32 v6, 1.0, v6
	v_div_fixup_f32 v5, v16, v5, 1.0
	v_div_scale_f32 v16, s[4:5], v6, v6, 1.0
	v_rcp_f32_e32 v17, v16
	v_exp_f32_e32 v7, v7
	s_waitcnt vmcnt(1)
; template <int MASK>
; __global__ void __launch_bounds__(256, 2) fwd_megakernel_t(Params p) {
;     ...
;             if (n0 >= C_GATE) {
;               const int br = (n0 - C_GATE) >> 11, ntg = ((n0 - C_GATE) & 2047) >> 7;
;               u16* gdst = gbuf + ((size_t)((((br * 128 + mt) * 16 + ntg) * 4 + wave) * 64 + lane)) * 64 + (i * 2 + j) * 16;
;               unsigned gw[8];
; #pragma unroll
;               for (int r = 0; r < 16; r += 2)
;                 gw[r >> 1] = pack2(1.f / (1.f + __expf(-acc[i][j][r] * rv[r])), 1.f / (1.f + __expf(-acc[i][j][r + 1] * rv[r + 1])));
;               *(uint4*)(gdst) = make_uint4(gw[0], gw[1], gw[2], gw[3]);
;               *(uint4*)(gdst + 8) = make_uint4(gw[4], gw[5], gw[6], gw[7]);
	v_mul_f32_e64 v8, v36, -v8
	v_mul_f32_e32 v8, 0x3fb8aa3b, v8
	v_fma_f32 v18, -v16, v17, 1.0
	v_fmac_f32_e32 v17, v18, v17
	v_div_scale_f32 v18, vcc, 1.0, v6, 1.0
	v_mul_f32_e32 v19, v18, v17
	v_fma_f32 v20, -v16, v19, v18
	v_fmac_f32_e32 v19, v20, v17
	v_fma_f32 v16, -v16, v19, v18
	v_div_fmas_f32 v16, v16, v17, v19
	v_add_f32_e32 v7, 1.0, v7
	v_div_fixup_f32 v6, v16, v6, 1.0
	v_div_scale_f32 v16, s[4:5], v7, v7, 1.0
	v_rcp_f32_e32 v17, v16
	v_exp_f32_e32 v8, v8
	v_mul_f32_e64 v9, v37, -v9
	v_mul_f32_e32 v9, 0x3fb8aa3b, v9
	v_fma_f32 v18, -v16, v17, 1.0
	v_fmac_f32_e32 v17, v18, v17
	v_div_scale_f32 v18, vcc, 1.0, v7, 1.0
	v_mul_f32_e32 v19, v18, v17
	v_fma_f32 v20, -v16, v19, v18
	v_fmac_f32_e32 v19, v20, v17
	v_fma_f32 v16, -v16, v19, v18
	v_div_fmas_f32 v16, v16, v17, v19
	v_add_f32_e32 v8, 1.0, v8
	v_div_fixup_f32 v7, v16, v7, 1.0
	v_div_scale_f32 v16, s[4:5], v8, v8, 1.0
	v_rcp_f32_e32 v17, v16
	v_exp_f32_e32 v9, v9
	v_mul_f32_e64 v10, v38, -v10
	v_mul_f32_e32 v10, 0x3fb8aa3b, v10
	v_fma_f32 v18, -v16, v17, 1.0
	v_fmac_f32_e32 v17, v18, v17
	v_div_scale_f32 v18, vcc, 1.0, v8, 1.0
	v_mul_f32_e32 v19, v18, v17
	v_fma_f32 v20, -v16, v19, v18
	v_fmac_f32_e32 v19, v20, v17
	v_fma_f32 v16, -v16, v19, v18
	v_div_fmas_f32 v16, v16, v17, v19
	v_add_f32_e32 v9, 1.0, v9
	v_div_fixup_f32 v8, v16, v8, 1.0
	v_div_scale_f32 v16, s[4:5], v9, v9, 1.0
	v_rcp_f32_e32 v17, v16
	v_exp_f32_e32 v10, v10
	v_mul_f32_e64 v11, v39, -v11
	v_mul_f32_e32 v11, 0x3fb8aa3b, v11
	v_fma_f32 v18, -v16, v17, 1.0
	v_fmac_f32_e32 v17, v18, v17
	v_div_scale_f32 v18, vcc, 1.0, v9, 1.0
	v_mul_f32_e32 v19, v18, v17
	v_fma_f32 v20, -v16, v19, v18
	v_fmac_f32_e32 v19, v20, v17
	v_fma_f32 v16, -v16, v19, v18
	v_div_fmas_f32 v16, v16, v17, v19
	v_add_f32_e32 v10, 1.0, v10
	v_div_fixup_f32 v9, v16, v9, 1.0
	v_div_scale_f32 v16, s[4:5], v10, v10, 1.0
	v_rcp_f32_e32 v17, v16
	v_exp_f32_e32 v11, v11
	s_waitcnt vmcnt(0)
	v_mul_f32_e64 v12, v32, -v12
	v_mul_f32_e32 v12, 0x3fb8aa3b, v12
	v_fma_f32 v18, -v16, v17, 1.0
	v_fmac_f32_e32 v17, v18, v17
	v_div_scale_f32 v18, vcc, 1.0, v10, 1.0
	v_mul_f32_e32 v19, v18, v17
	v_fma_f32 v20, -v16, v19, v18
	v_fmac_f32_e32 v19, v20, v17
	v_fma_f32 v16, -v16, v19, v18
	v_div_fmas_f32 v16, v16, v17, v19
	v_add_f32_e32 v11, 1.0, v11
	v_div_fixup_f32 v10, v16, v10, 1.0
	v_div_scale_f32 v16, s[4:5], v11, v11, 1.0
	v_rcp_f32_e32 v17, v16
	v_exp_f32_e32 v12, v12
	v_mul_f32_e64 v13, v33, -v13
	v_mul_f32_e32 v13, 0x3fb8aa3b, v13
	v_fma_f32 v18, -v16, v17, 1.0
	v_fmac_f32_e32 v17, v18, v17
	v_div_scale_f32 v18, vcc, 1.0, v11, 1.0
	v_mul_f32_e32 v19, v18, v17
	v_fma_f32 v20, -v16, v19, v18
	v_fmac_f32_e32 v19, v20, v17
	v_fma_f32 v16, -v16, v19, v18
	v_div_fmas_f32 v16, v16, v17, v19
	v_add_f32_e32 v12, 1.0, v12
	v_div_fixup_f32 v11, v16, v11, 1.0
	v_div_scale_f32 v16, s[4:5], v12, v12, 1.0
	v_rcp_f32_e32 v17, v16
	v_exp_f32_e32 v13, v13
	v_mul_f32_e64 v14, v34, -v14
	v_mul_f32_e32 v14, 0x3fb8aa3b, v14
	v_fma_f32 v18, -v16, v17, 1.0
	v_fmac_f32_e32 v17, v18, v17
	v_div_scale_f32 v18, vcc, 1.0, v12, 1.0
	v_mul_f32_e32 v19, v18, v17
	v_fma_f32 v20, -v16, v19, v18
	v_fmac_f32_e32 v19, v20, v17
	v_fma_f32 v16, -v16, v19, v18
	v_div_fmas_f32 v16, v16, v17, v19
	v_add_f32_e32 v13, 1.0, v13
	v_div_fixup_f32 v12, v16, v12, 1.0
	v_div_scale_f32 v16, s[4:5], v13, v13, 1.0
	v_rcp_f32_e32 v17, v16
	v_exp_f32_e32 v14, v14
	v_mul_f32_e64 v15, v35, -v15
	v_mul_f32_e32 v15, 0x3fb8aa3b, v15
	v_fma_f32 v18, -v16, v17, 1.0
	v_fmac_f32_e32 v17, v18, v17
	v_div_scale_f32 v18, vcc, 1.0, v13, 1.0
	v_mul_f32_e32 v19, v18, v17
	v_fma_f32 v20, -v16, v19, v18
	v_fmac_f32_e32 v19, v20, v17
	v_fma_f32 v16, -v16, v19, v18
	v_div_fmas_f32 v16, v16, v17, v19
	v_add_f32_e32 v14, 1.0, v14
	v_div_fixup_f32 v13, v16, v13, 1.0
	v_div_scale_f32 v16, s[4:5], v14, v14, 1.0
	v_rcp_f32_e32 v17, v16
	v_exp_f32_e32 v15, v15
	v_cvt_pk_bf16_f32 v7, v6, v7
	v_cvt_pk_bf16_f32 v6, v4, v5
	v_fma_f32 v18, -v16, v17, 1.0
	v_fmac_f32_e32 v17, v18, v17
	v_div_scale_f32 v18, vcc, 1.0, v14, 1.0
	v_mul_f32_e32 v19, v18, v17
	v_fma_f32 v20, -v16, v19, v18
	v_fmac_f32_e32 v19, v20, v17
	v_fma_f32 v16, -v16, v19, v18
	v_div_fmas_f32 v16, v16, v17, v19
	v_add_f32_e32 v15, 1.0, v15
	v_div_fixup_f32 v14, v16, v14, 1.0
	v_div_scale_f32 v16, s[4:5], v15, v15, 1.0
	v_rcp_f32_e32 v17, v16
	v_cvt_pk_bf16_f32 v5, v2, v3
	v_cvt_pk_bf16_f32 v4, v0, v1
	v_cvt_pk_bf16_f32 v2, v12, v13
	v_fma_f32 v18, -v16, v17, 1.0
	v_fmac_f32_e32 v17, v18, v17
	v_div_scale_f32 v18, vcc, 1.0, v15, 1.0
	v_mul_f32_e32 v19, v18, v17
	v_fma_f32 v20, -v16, v19, v18
	v_fmac_f32_e32 v19, v20, v17
	v_fma_f32 v16, -v16, v19, v18
	v_div_fmas_f32 v16, v16, v17, v19
	v_div_fixup_f32 v15, v16, v15, 1.0
	v_cvt_pk_bf16_f32 v3, v14, v15
	v_cvt_pk_bf16_f32 v1, v10, v11
	v_cvt_pk_bf16_f32 v0, v8, v9
	global_store_dwordx4 v[80:81], v[4:7], off offset:2048
	global_store_dwordx4 v[80:81], v[0:3], off offset:3072

; template <int MASK>
; __global__ void __launch_bounds__(256, 2) fwd_megakernel_t(Params p) {
;     ...
;             if (n0 >= C_GATE) {
;               const int br = (n0 - C_GATE) >> 11, ntg = ((n0 - C_GATE) & 2047) >> 7;
;               u16* gdst = gbuf + ((size_t)((((br * 128 + mt) * 16 + ntg) * 4 + wave) * 64 + lane)) * 64 + (i * 2 + j) * 16;
;               unsigned gw[8];
; #pragma unroll
;               for (int r = 0; r < 16; r += 2)
;                 gw[r >> 1] = pack2(1.f / (1.f + __expf(-acc[i][j][r] * rv[r])), 1.f / (1.f + __expf(-acc[i][j][r + 1] * rv[r + 1])));
;               *(uint4*)(gdst) = make_uint4(gw[0], gw[1], gw[2], gw[3]);
;               *(uint4*)(gdst + 8) = make_uint4(gw[4], gw[5], gw[6], gw[7]);
.LBB0_788:
	s_waitcnt vmcnt(3)
	v_mul_f32_e64 v16, v44, -v16
	v_mul_f32_e32 v16, 0x3fb8aa3b, v16
	v_exp_f32_e32 v16, v16
	v_mul_f32_e64 v17, v45, -v17
	v_mul_f32_e32 v17, 0x3fb8aa3b, v17
	v_exp_f32_e32 v17, v17
	v_add_f32_e32 v16, 1.0, v16
	v_div_scale_f32 v49, s[16:17], v16, v16, 1.0
	v_rcp_f32_e32 v58, v49
	v_add_f32_e32 v17, 1.0, v17
	v_mul_f32_e64 v18, v46, -v18
	v_mul_f32_e32 v18, 0x3fb8aa3b, v18
	v_fma_f32 v59, -v49, v58, 1.0
	v_fmac_f32_e32 v58, v59, v58
	v_div_scale_f32 v59, vcc, 1.0, v16, 1.0
	v_mul_f32_e32 v69, v59, v58
	v_fma_f32 v70, -v49, v69, v59
	v_fmac_f32_e32 v69, v70, v58
	v_fma_f32 v49, -v49, v69, v59
	v_div_fmas_f32 v49, v49, v58, v69
	v_div_fixup_f32 v16, v49, v16, 1.0
	v_div_scale_f32 v49, s[16:17], v17, v17, 1.0
	v_rcp_f32_e32 v58, v49
	v_exp_f32_e32 v18, v18
	v_mul_f32_e64 v19, v47, -v19
	v_mul_f32_e32 v19, 0x3fb8aa3b, v19
	v_fma_f32 v59, -v49, v58, 1.0
	v_fmac_f32_e32 v58, v59, v58
	v_div_scale_f32 v59, vcc, 1.0, v17, 1.0
	v_mul_f32_e32 v69, v59, v58
	v_fma_f32 v70, -v49, v69, v59
	v_fmac_f32_e32 v69, v70, v58
	v_fma_f32 v49, -v49, v69, v59
	v_div_fmas_f32 v49, v49, v58, v69
	v_add_f32_e32 v18, 1.0, v18
	v_div_fixup_f32 v17, v49, v17, 1.0
	v_div_scale_f32 v49, s[16:17], v18, v18, 1.0
	v_rcp_f32_e32 v58, v49
	v_exp_f32_e32 v19, v19
	s_waitcnt vmcnt(2)
	v_mul_f32_e64 v20, v40, -v20
	v_mul_f32_e32 v20, 0x3fb8aa3b, v20
	v_fma_f32 v59, -v49, v58, 1.0
	v_fmac_f32_e32 v58, v59, v58
	v_div_scale_f32 v59, vcc, 1.0, v18, 1.0
	v_mul_f32_e32 v69, v59, v58
	v_fma_f32 v70, -v49, v69, v59
	v_fmac_f32_e32 v69, v70, v58
	v_fma_f32 v49, -v49, v69, v59
	v_div_fmas_f32 v49, v49, v58, v69
	v_add_f32_e32 v19, 1.0, v19
	v_div_fixup_f32 v18, v49, v18, 1.0
	v_div_scale_f32 v49, s[16:17], v19, v19, 1.0
	v_rcp_f32_e32 v58, v49
	v_exp_f32_e32 v20, v20
	v_mul_f32_e64 v21, v41, -v21
	v_mul_f32_e32 v21, 0x3fb8aa3b, v21
	v_fma_f32 v59, -v49, v58, 1.0
	v_fmac_f32_e32 v58, v59, v58
	v_div_scale_f32 v59, vcc, 1.0, v19, 1.0
	v_mul_f32_e32 v69, v59, v58
	v_fma_f32 v70, -v49, v69, v59
	v_fmac_f32_e32 v69, v70, v58
	v_fma_f32 v49, -v49, v69, v59
	v_div_fmas_f32 v49, v49, v58, v69
	v_add_f32_e32 v20, 1.0, v20
	v_div_fixup_f32 v19, v49, v19, 1.0
	v_div_scale_f32 v49, s[16:17], v20, v20, 1.0
	v_rcp_f32_e32 v58, v49
	v_exp_f32_e32 v21, v21
	v_mul_f32_e64 v22, v42, -v22
	v_mul_f32_e32 v22, 0x3fb8aa3b, v22
	v_fma_f32 v59, -v49, v58, 1.0
	v_fmac_f32_e32 v58, v59, v58
	v_div_scale_f32 v59, vcc, 1.0, v20, 1.0
	v_mul_f32_e32 v69, v59, v58
	v_fma_f32 v70, -v49, v69, v59
	v_fmac_f32_e32 v69, v70, v58
	v_fma_f32 v49, -v49, v69, v59
	v_div_fmas_f32 v49, v49, v58, v69
	v_add_f32_e32 v21, 1.0, v21
	v_div_fixup_f32 v20, v49, v20, 1.0
	v_div_scale_f32 v49, s[16:17], v21, v21, 1.0
	v_rcp_f32_e32 v58, v49
	v_exp_f32_e32 v22, v22
	v_mul_f32_e64 v23, v43, -v23
	v_mul_f32_e32 v23, 0x3fb8aa3b, v23
	v_fma_f32 v59, -v49, v58, 1.0
	v_fmac_f32_e32 v58, v59, v58
	v_div_scale_f32 v59, vcc, 1.0, v21, 1.0
	v_mul_f32_e32 v69, v59, v58
	v_fma_f32 v70, -v49, v69, v59
	v_fmac_f32_e32 v69, v70, v58
	v_fma_f32 v49, -v49, v69, v59
	v_div_fmas_f32 v49, v49, v58, v69
	v_add_f32_e32 v22, 1.0, v22
	v_div_fixup_f32 v21, v49, v21, 1.0
	v_div_scale_f32 v49, s[16:17], v22, v22, 1.0
	v_rcp_f32_e32 v58, v49
	v_exp_f32_e32 v23, v23
	s_waitcnt vmcnt(1)
; template <int MASK>
; __global__ void __launch_bounds__(256, 2) fwd_megakernel_t(Params p) {
;     ...
;             if (n0 >= C_GATE) {
;               const int br = (n0 - C_GATE) >> 11, ntg = ((n0 - C_GATE) & 2047) >> 7;
;               u16* gdst = gbuf + ((size_t)((((br * 128 + mt) * 16 + ntg) * 4 + wave) * 64 + lane)) * 64 + (i * 2 + j) * 16;
;               unsigned gw[8];
; #pragma unroll
;               for (int r = 0; r < 16; r += 2)
;                 gw[r >> 1] = pack2(1.f / (1.f + __expf(-acc[i][j][r] * rv[r])), 1.f / (1.f + __expf(-acc[i][j][r + 1] * rv[r + 1])));
;               *(uint4*)(gdst) = make_uint4(gw[0], gw[1], gw[2], gw[3]);
;               *(uint4*)(gdst + 8) = make_uint4(gw[4], gw[5], gw[6], gw[7]);
	v_mul_f32_e64 v24, v36, -v24
	v_mul_f32_e32 v24, 0x3fb8aa3b, v24
	v_fma_f32 v59, -v49, v58, 1.0
	v_fmac_f32_e32 v58, v59, v58
	v_div_scale_f32 v59, vcc, 1.0, v22, 1.0
	v_mul_f32_e32 v69, v59, v58
	v_fma_f32 v70, -v49, v69, v59
	v_fmac_f32_e32 v69, v70, v58
	v_fma_f32 v49, -v49, v69, v59
	v_div_fmas_f32 v49, v49, v58, v69
	v_add_f32_e32 v23, 1.0, v23
	v_div_fixup_f32 v22, v49, v22, 1.0
	v_div_scale_f32 v49, s[16:17], v23, v23, 1.0
	v_rcp_f32_e32 v58, v49
	v_exp_f32_e32 v24, v24
	v_mul_f32_e64 v25, v37, -v25
	v_mul_f32_e32 v25, 0x3fb8aa3b, v25
	v_fma_f32 v59, -v49, v58, 1.0
	v_fmac_f32_e32 v58, v59, v58
	v_div_scale_f32 v59, vcc, 1.0, v23, 1.0
	v_mul_f32_e32 v69, v59, v58
	v_fma_f32 v70, -v49, v69, v59
	v_fmac_f32_e32 v69, v70, v58
	v_fma_f32 v49, -v49, v69, v59
	v_div_fmas_f32 v49, v49, v58, v69
	v_add_f32_e32 v24, 1.0, v24
	v_div_fixup_f32 v23, v49, v23, 1.0
	v_div_scale_f32 v49, s[16:17], v24, v24, 1.0
	v_rcp_f32_e32 v58, v49
	v_exp_f32_e32 v25, v25
	v_mul_f32_e64 v26, v38, -v26
	v_mul_f32_e32 v26, 0x3fb8aa3b, v26
	v_fma_f32 v59, -v49, v58, 1.0
	v_fmac_f32_e32 v58, v59, v58
	v_div_scale_f32 v59, vcc, 1.0, v24, 1.0
	v_mul_f32_e32 v69, v59, v58
	v_fma_f32 v70, -v49, v69, v59
	v_fmac_f32_e32 v69, v70, v58
	v_fma_f32 v49, -v49, v69, v59
	v_div_fmas_f32 v49, v49, v58, v69
	v_add_f32_e32 v25, 1.0, v25
	v_div_fixup_f32 v24, v49, v24, 1.0
	v_div_scale_f32 v49, s[16:17], v25, v25, 1.0
	v_rcp_f32_e32 v58, v49
	v_exp_f32_e32 v26, v26
	v_mul_f32_e64 v27, v39, -v27
	v_mul_f32_e32 v27, 0x3fb8aa3b, v27
	v_fma_f32 v59, -v49, v58, 1.0
	v_fmac_f32_e32 v58, v59, v58
	v_div_scale_f32 v59, vcc, 1.0, v25, 1.0
	v_mul_f32_e32 v69, v59, v58
	v_fma_f32 v70, -v49, v69, v59
	v_fmac_f32_e32 v69, v70, v58
	v_fma_f32 v49, -v49, v69, v59
	v_div_fmas_f32 v49, v49, v58, v69
	v_add_f32_e32 v26, 1.0, v26
	v_div_fixup_f32 v25, v49, v25, 1.0
	v_div_scale_f32 v49, s[16:17], v26, v26, 1.0
	v_rcp_f32_e32 v58, v49
	v_exp_f32_e32 v27, v27
	s_waitcnt vmcnt(0)
	v_mul_f32_e64 v28, v32, -v28
	v_mul_f32_e32 v28, 0x3fb8aa3b, v28
	v_fma_f32 v59, -v49, v58, 1.0
	v_fmac_f32_e32 v58, v59, v58
	v_div_scale_f32 v59, vcc, 1.0, v26, 1.0
	v_mul_f32_e32 v69, v59, v58
	v_fma_f32 v70, -v49, v69, v59
	v_fmac_f32_e32 v69, v70, v58
	v_fma_f32 v49, -v49, v69, v59
	v_div_fmas_f32 v49, v49, v58, v69
	v_add_f32_e32 v27, 1.0, v27
	v_div_fixup_f32 v26, v49, v26, 1.0
	v_div_scale_f32 v49, s[16:17], v27, v27, 1.0
	v_rcp_f32_e32 v58, v49
	v_exp_f32_e32 v28, v28
	v_mul_f32_e64 v29, v33, -v29
	v_mul_f32_e32 v29, 0x3fb8aa3b, v29
	v_fma_f32 v59, -v49, v58, 1.0
	v_fmac_f32_e32 v58, v59, v58
	v_div_scale_f32 v59, vcc, 1.0, v27, 1.0
	v_mul_f32_e32 v69, v59, v58
	v_fma_f32 v70, -v49, v69, v59
	v_fmac_f32_e32 v69, v70, v58
	v_fma_f32 v49, -v49, v69, v59
	v_div_fmas_f32 v49, v49, v58, v69
	v_add_f32_e32 v28, 1.0, v28
	v_div_fixup_f32 v27, v49, v27, 1.0
	v_div_scale_f32 v49, s[16:17], v28, v28, 1.0
	v_rcp_f32_e32 v58, v49
	v_exp_f32_e32 v29, v29
	v_mul_f32_e64 v30, v34, -v30
	v_mul_f32_e32 v30, 0x3fb8aa3b, v30
	v_fma_f32 v59, -v49, v58, 1.0
	v_fmac_f32_e32 v58, v59, v58
	v_div_scale_f32 v59, vcc, 1.0, v28, 1.0
	v_mul_f32_e32 v69, v59, v58
	v_fma_f32 v70, -v49, v69, v59
	v_fmac_f32_e32 v69, v70, v58
	v_fma_f32 v49, -v49, v69, v59
	v_div_fmas_f32 v49, v49, v58, v69
	v_add_f32_e32 v29, 1.0, v29
	v_div_fixup_f32 v28, v49, v28, 1.0
	v_div_scale_f32 v49, s[16:17], v29, v29, 1.0
	v_rcp_f32_e32 v58, v49
	v_exp_f32_e32 v30, v30
	v_mul_f32_e64 v31, v35, -v31
	v_mul_f32_e32 v31, 0x3fb8aa3b, v31
	v_fma_f32 v59, -v49, v58, 1.0
	v_fmac_f32_e32 v58, v59, v58
	v_div_scale_f32 v59, vcc, 1.0, v29, 1.0
	v_mul_f32_e32 v69, v59, v58
	v_fma_f32 v70, -v49, v69, v59
	v_fmac_f32_e32 v69, v70, v58
	v_fma_f32 v49, -v49, v69, v59
	v_div_fmas_f32 v49, v49, v58, v69
	v_add_f32_e32 v30, 1.0, v30
	v_div_fixup_f32 v29, v49, v29, 1.0
	v_div_scale_f32 v49, s[16:17], v30, v30, 1.0
	v_rcp_f32_e32 v58, v49
	v_exp_f32_e32 v31, v31
	v_cvt_pk_bf16_f32 v23, v22, v23
	v_cvt_pk_bf16_f32 v22, v20, v21
	v_fma_f32 v59, -v49, v58, 1.0
	v_fmac_f32_e32 v58, v59, v58
	v_div_scale_f32 v59, vcc, 1.0, v30, 1.0
	v_mul_f32_e32 v69, v59, v58
	v_fma_f32 v70, -v49, v69, v59
	v_fmac_f32_e32 v69, v70, v58
	v_fma_f32 v49, -v49, v69, v59
	v_div_fmas_f32 v49, v49, v58, v69
	v_add_f32_e32 v31, 1.0, v31
	v_div_fixup_f32 v30, v49, v30, 1.0
	v_div_scale_f32 v49, s[16:17], v31, v31, 1.0
	v_rcp_f32_e32 v58, v49
	v_cvt_pk_bf16_f32 v21, v18, v19
	v_cvt_pk_bf16_f32 v20, v16, v17
	v_cvt_pk_bf16_f32 v18, v28, v29
	v_fma_f32 v59, -v49, v58, 1.0
	v_fmac_f32_e32 v58, v59, v58
	v_div_scale_f32 v59, vcc, 1.0, v31, 1.0
	v_mul_f32_e32 v69, v59, v58
	v_fma_f32 v70, -v49, v69, v59
	v_fmac_f32_e32 v69, v70, v58
	v_fma_f32 v49, -v49, v69, v59
	v_div_fmas_f32 v49, v49, v58, v69
	v_div_fixup_f32 v31, v49, v31, 1.0
	v_cvt_pk_bf16_f32 v19, v30, v31
	v_cvt_pk_bf16_f32 v17, v26, v27
	v_cvt_pk_bf16_f32 v16, v24, v25
	global_store_dwordx4 v[80:81], v[20:23], off offset:0
	global_store_dwordx4 v[80:81], v[16:19], off offset:1024
	s_and_b64 vcc, exec, s[6:7]
	s_mov_b64 s[6:7], -1
	s_cbranch_vccnz .LBB0_769
